# All 4 GEMM K-loops: first K-iteration peeled with C=0 MFMAs (no acc zeroing moves); GU epilogue counted vmcnt(8) instead of vmcnt(0)
# speedup vs baseline: 1.0141x; 1.0090x over previous
;     __device__ __forceinline__ Pre prefetch(const Unit& u, int tid) const { return prenorm_load(stats, u.pn * BM, sW + (size_t)(u.pn >> 4) * SW_ROWS + u.pm * BM, tid); }
;     __device__ __forceinline__ Pre prefetch(const Unit& u, int tid) const { return prenorm_load(stats, u.pm * BM, sW + (size_t)(u.pm >> 4) * SW_ROWS + u.pn * BM, tid); }
;     __device__ __forceinline__ Pre prefetch(const Unit& u, int tid) const { return prenorm_load(stats, u.pm * BM, sW + (size_t)(u.pm >> 4) * SW_ROWS + u.pn * BM, tid); }
; #define PG8_STAGE(bufoff, gbase, voff) do { _Pragma("unroll") for (int _i = 0; _i < 2; ++_i) \
;         __builtin_amdgcn_global_load_lds((const unsigned*)((const char*)(gbase) + (voff)[_i]), (LAS unsigned*)(lds + (bufoff) + ldsw + _i * 8192), 16, 0, 0); } while (0)
; __device__ __forceinline__ PreNorm prenorm_load(const float* stats, int row0, const float* swp, int tid) {
;     PreNorm p; p.st = (f32x4){0.f, 0.f, 0.f, 0.f}; p.sw = 0.f;
;     if (tid < 256) { p.st = *(const f32x4*)(stats + (size_t)(row0 + tid) * 4); p.sw = swp[tid]; }
;     return p;
; template <class Epi, class Sched>
; __device__ __forceinline__ void gemm_phase(LAS unsigned char* lds, const Gemm g, const Sched& S, const Epi& E, const int tid) {
;     ...
;         const bool has_next = S.next(ui + 1, nxt);
;         const char* nA = has_next ? (const char*)g.A + (size_t)nxt.pm * tstep : cA; const char* nB = has_next ? (const char*)g.Bt + (size_t)nxt.pn * tstep : cB;
;         const typename Epi::Pre pre = E.prefetch(cur, tid);
;         for (int t = 0; t < nt; t += 2) {
;             const bool last = (t == nt - 2);
;             const char* a1 = cA + (size_t)(t + 1) * kstep;
;             const char* a2 = last ? nA : cA + (size_t)(t + 2) * kstep; const char* b2 = last ? nB : cB + (size_t)(t + 2) * kstep;
;             const char* a3 = a2 + kstep; const char* b3 = b2 + kstep;
;             PG8_LDB(B0, 0, 0); PG8_LDB(B1, 0, 1); PG8_SCHED; PG8_LDA(At, 0, 0); PG8_STAGE(PG8_SA(1, 1), a1 + hstep, voffA);
;             PG8_WAIT_V(8); PG8_WAIT_L(0); PG8_BAR; PG8_MMA(0, 0, At, B0); PG8_MMA(0, 1, At, B1); PG8_BAR; PG8_SCHED;
;             PG8_LDA(At, 0, 1); PG8_STAGE(PG8_SB(0, 0), b2, voffB); PG8_STAGE(PG8_SB(0, 1), b2 + hstep, voffB); PG8_STAGE(PG8_SA(0, 0), a2, voffA);
;             PG8_WAIT_V(8); PG8_WAIT_L(0); PG8_BAR; PG8_MMA(1, 0, At, B0); PG8_MMA(1, 1, At, B1); PG8_BAR; PG8_SCHED;
.LBB0_165:
	v_mov_b32_e32 v144, 0
	v_mov_b32_e32 v112, 0
	v_mov_b32_e32 v113, 0
	v_mov_b32_e32 v114, 0
	v_mov_b32_e32 v115, 0
	s_and_saveexec_b64 s[22:23], s[4:5]
	s_cbranch_execz .LBB0_167
	s_ashr_i32 s38, s52, 4
	s_mul_hi_i32 s39, s38, 0xd800
	s_mul_i32 s38, s38, 0xd800
	s_add_u32 s55, s91, s38
	s_addc_u32 s56, s92, s39
	s_lshl_b32 s38, s53, 8
	s_ashr_i32 s39, s38, 31
	v_lshl_add_u32 v2, s52, 8, v132
	s_lshl_b64 s[38:39], s[38:39], 2
	v_ashrrev_i32_e32 v3, 31, v2
	s_add_u32 s38, s55, s38
	v_lshl_add_u64 v[2:3], v[2:3], 4, s[40:41]
	s_addc_u32 s39, s56, s39
	v_lshl_add_u64 v[4:5], v[132:133], 2, s[38:39]
	global_load_dwordx4 v[112:115], v[2:3], off
	global_load_dword v144, v[4:5], off
.LBB0_167:
	s_or_b64 exec, exec, s[22:23]
	s_ashr_i32 s55, s54, 31
	s_lshl_b64 s[22:23], s[54:55], 19
	s_add_u32 s22, s46, s22
	s_addc_u32 s23, s47, s23
	s_and_b64 s[38:39], s[6:7], exec
	s_cselect_b32 s55, s23, s65
	s_cselect_b32 s56, s22, s64
	s_ashr_i32 s63, s62, 31
	s_lshl_b64 s[38:39], s[62:63], 19
	s_add_u32 s38, s12, s38
	s_addc_u32 s39, s73, s39
	s_and_b64 s[58:59], s[6:7], exec
	s_cselect_b32 s57, s39, s67
	s_cselect_b32 s58, s38, s66
	s_add_u32 s64, s64, 0x40080
	s_addc_u32 s65, s65, 0
	s_add_u32 s59, s66, 0x100
	s_addc_u32 s60, s67, 0
	s_mov_b32 s61, -2
	s_add_u32 s63, s64, 0xfffc0080
	s_addc_u32 s66, s65, -1
	s_add_i32 s78, 0, 0x10000
	s_cmp_eq_u32 s61, 12
	s_cselect_b32 s71, s55, s66
	s_cselect_b32 s70, s56, s63
	v_add_u32_e32 v145, s78, v166
	s_cselect_b32 s67, s57, s60
	s_cselect_b32 s66, s58, s59
	s_add_i32 s63, 0, 0x14000
	ds_read_b128 v[146:149], v145
	ds_read_b128 v[150:153], v145 offset:1024
	ds_read_b128 v[154:157], v145 offset:2048
	ds_read_b128 v[158:161], v145 offset:3072
	v_add_u32_e32 v145, s63, v166
	ds_read_b128 v[172:175], v145
	ds_read_b128 v[176:179], v145 offset:1024
	ds_read_b128 v[180:183], v145 offset:2048
	ds_read_b128 v[184:187], v145 offset:3072
	v_lshl_add_u64 v[162:163], s[64:65], 0, v[140:141]
	s_add_i32 m0, s75, 0xc000
	ds_read_b128 v[188:191], v171
	ds_read_b128 v[198:201], v171 offset:1024
	ds_read_b128 v[202:205], v171 offset:2048
	ds_read_b128 v[206:209], v171 offset:3072
	ds_read_b128 v[210:213], v171 offset:4096
	ds_read_b128 v[214:217], v171 offset:5120
	ds_read_b128 v[218:221], v171 offset:6144
	ds_read_b128 v[230:233], v171 offset:7168
	global_load_lds_dwordx4 v[162:163], off
	v_lshl_add_u64 v[162:163], s[64:65], 0, v[142:143]
	s_add_i32 m0, s75, 0xe000
	s_nop 0
	global_load_lds_dwordx4 v[162:163], off
	s_waitcnt vmcnt(8)
	s_waitcnt lgkmcnt(0)
	s_barrier
	s_setprio 1
	s_waitcnt lgkmcnt(0)
	v_mfma_f32_16x16x32_bf16 v[128:131], v[146:149], v[188:191], 0
	v_mfma_f32_16x16x32_bf16 v[124:127], v[154:157], v[188:191], 0
	v_mfma_f32_16x16x32_bf16 v[108:111], v[146:149], v[202:205], 0
	v_mfma_f32_16x16x32_bf16 v[104:107], v[154:157], v[202:205], 0
	v_mfma_f32_16x16x32_bf16 v[92:95], v[146:149], v[210:213], 0
	v_mfma_f32_16x16x32_bf16 v[88:91], v[154:157], v[210:213], 0
	v_mfma_f32_16x16x32_bf16 v[76:79], v[146:149], v[218:221], 0
	v_mfma_f32_16x16x32_bf16 v[72:75], v[154:157], v[218:221], 0
	v_mfma_f32_16x16x32_bf16 v[128:131], v[150:153], v[198:201], v[128:131]
	v_mfma_f32_16x16x32_bf16 v[124:127], v[158:161], v[198:201], v[124:127]
	v_mfma_f32_16x16x32_bf16 v[108:111], v[150:153], v[206:209], v[108:111]
	v_mfma_f32_16x16x32_bf16 v[104:107], v[158:161], v[206:209], v[104:107]
	v_mfma_f32_16x16x32_bf16 v[92:95], v[150:153], v[214:217], v[92:95]
	v_mfma_f32_16x16x32_bf16 v[88:91], v[158:161], v[214:217], v[88:91]
	v_mfma_f32_16x16x32_bf16 v[76:79], v[150:153], v[230:233], v[76:79]
	v_mfma_f32_16x16x32_bf16 v[72:75], v[158:161], v[230:233], v[72:75]
	s_setprio 0
	s_setprio 1
	v_mfma_f32_16x16x32_bf16 v[120:123], v[172:175], v[188:191], 0
	v_mfma_f32_16x16x32_bf16 v[116:119], v[180:183], v[188:191], 0
	v_mfma_f32_16x16x32_bf16 v[100:103], v[172:175], v[202:205], 0
	v_mfma_f32_16x16x32_bf16 v[96:99], v[180:183], v[202:205], 0
	v_mfma_f32_16x16x32_bf16 v[84:87], v[172:175], v[210:213], 0
	v_mfma_f32_16x16x32_bf16 v[80:83], v[180:183], v[210:213], 0
	v_mfma_f32_16x16x32_bf16 v[68:71], v[172:175], v[218:221], 0
	v_mfma_f32_16x16x32_bf16 v[64:67], v[180:183], v[218:221], 0
	v_mfma_f32_16x16x32_bf16 v[120:123], v[176:179], v[198:201], v[120:123]
	v_mfma_f32_16x16x32_bf16 v[116:119], v[184:187], v[198:201], v[116:119]
	v_mfma_f32_16x16x32_bf16 v[100:103], v[176:179], v[206:209], v[100:103]
	v_mfma_f32_16x16x32_bf16 v[96:99], v[184:187], v[206:209], v[96:99]
	v_mfma_f32_16x16x32_bf16 v[84:87], v[176:179], v[214:217], v[84:87]
	v_mfma_f32_16x16x32_bf16 v[80:83], v[184:187], v[214:217], v[80:83]
	v_mfma_f32_16x16x32_bf16 v[68:71], v[176:179], v[230:233], v[68:71]
	v_mfma_f32_16x16x32_bf16 v[64:67], v[184:187], v[230:233], v[64:67]
	s_setprio 0
	s_barrier
	s_add_i32 s78, s78, s74
	v_lshl_add_u64 v[162:163], s[66:67], 0, v[192:193]
	s_mov_b32 m0, s78
	ds_read_b128 v[188:191], v171 offset:16384
	ds_read_b128 v[198:201], v171 offset:17408
	ds_read_b128 v[202:205], v171 offset:18432
	ds_read_b128 v[206:209], v171 offset:19456
	ds_read_b128 v[210:213], v171 offset:20480
	ds_read_b128 v[214:217], v171 offset:21504
	ds_read_b128 v[218:221], v171 offset:22528
	ds_read_b128 v[230:233], v171 offset:23552
	global_load_lds_dwordx4 v[162:163], off
	s_add_i32 m0, s78, 0x2000
	s_add_u32 s78, s66, 0x40000
	v_lshl_add_u64 v[234:235], s[66:67], 0, v[134:135]
	s_addc_u32 s79, s67, 0
	s_add_i32 s63, s63, s74
	global_load_lds_dwordx4 v[234:235], off
	v_lshl_add_u64 v[236:237], s[78:79], 0, v[192:193]
	s_mov_b32 m0, s63
	v_lshl_add_u64 v[238:239], s[70:71], 0, v[136:137]
	global_load_lds_dwordx4 v[236:237], off
	v_lshl_add_u64 v[236:237], s[78:79], 0, v[134:135]
	s_add_i32 m0, s63, 0x2000
	s_nop 0
	global_load_lds_dwordx4 v[236:237], off
	v_lshl_add_u64 v[236:237], s[70:71], 0, v[138:139]
	s_mov_b32 m0, s75
	s_nop 0
	global_load_lds_dwordx4 v[236:237], off
	s_mov_b32 m0, s81
	s_nop 0
	global_load_lds_dwordx4 v[238:239], off
	s_waitcnt vmcnt(8)
	s_waitcnt lgkmcnt(0)
	s_barrier
; #define PG8_STAGE(bufoff, gbase, voff) do { _Pragma("unroll") for (int _i = 0; _i < 2; ++_i) \
;         __builtin_amdgcn_global_load_lds((const unsigned*)((const char*)(gbase) + (voff)[_i]), (LAS unsigned*)(lds + (bufoff) + ldsw + _i * 8192), 16, 0, 0); } while (0)
; #define PG8_LDA(dst, b, h) do { _Pragma("unroll") for (int m = 0; m < 4; ++m) _Pragma("unroll") for (int k = 0; k < 2; ++k) dst[m][k] = *(const LAS bf16x8*)(lds + PG8_SA(b, h) + aoff + m * 2048 + k * 1024); } while (0)
; #define PG8_LDB(dst, b, h) do { _Pragma("unroll") for (int n = 0; n < 2; ++n) _Pragma("unroll") for (int k = 0; k < 2; ++k) dst[n][k] = *(const LAS bf16x8*)(lds + PG8_SB(b, h) + boff + n * 2048 + k * 1024); } while (0)
; #define PG8_MMA(ai, bj, At, Bt) do { __builtin_amdgcn_s_setprio(1); _Pragma("unroll") for (int m = 0; m < 4; ++m) _Pragma("unroll") for (int n = 0; n < 2; ++n) _Pragma("unroll") for (int k = 0; k < 2; ++k) \
;         acc[ai][bj][m][n] = __builtin_amdgcn_mfma_f32_16x16x32_bf16(Bt[n][k], At[m][k], acc[ai][bj][m][n], 0, 0, 0); __builtin_amdgcn_s_setprio(0); } while (0)
; #define PG8_WAIT_V(n) asm volatile("s_waitcnt vmcnt(" #n ")" ::: "memory")
; #define PG8_WAIT_L(n) asm volatile("s_waitcnt lgkmcnt(" #n ")" ::: "memory")
; #define PG8_BAR __builtin_amdgcn_s_barrier()
; #define PG8_SCHED __builtin_amdgcn_sched_barrier(0)
; template <class Epi, class Sched>
; __device__ __forceinline__ void gemm_phase(LAS unsigned char* lds, const Gemm g, const Sched& S, const Epi& E, const int tid) {
;     ...
;             PG8_WAIT_V(8); PG8_WAIT_L(0); PG8_BAR; PG8_MMA(1, 0, At, B0); PG8_MMA(1, 1, At, B1); PG8_BAR; PG8_SCHED;
;             PG8_LDB(B0, 1, 0); PG8_LDB(B1, 1, 1); PG8_SCHED; PG8_LDA(At, 1, 0); PG8_STAGE(PG8_SA(0, 1), a2 + hstep, voffA);
;             PG8_WAIT_V(8); PG8_WAIT_L(0); PG8_BAR; PG8_MMA(0, 0, At, B0); PG8_MMA(0, 1, At, B1); PG8_BAR; PG8_SCHED;
	s_setprio 1
	s_waitcnt lgkmcnt(0)
	v_mfma_f32_16x16x32_bf16 v[60:63], v[146:149], v[188:191], 0
	v_mfma_f32_16x16x32_bf16 v[56:59], v[154:157], v[188:191], 0
	v_mfma_f32_16x16x32_bf16 v[44:47], v[146:149], v[202:205], 0
	v_mfma_f32_16x16x32_bf16 v[40:43], v[154:157], v[202:205], 0
	v_mfma_f32_16x16x32_bf16 v[28:31], v[146:149], v[210:213], 0
	v_mfma_f32_16x16x32_bf16 v[24:27], v[154:157], v[210:213], 0
	v_mfma_f32_16x16x32_bf16 v[12:15], v[146:149], v[218:221], 0
	v_mfma_f32_16x16x32_bf16 v[8:11], v[154:157], v[218:221], 0
	v_mfma_f32_16x16x32_bf16 v[60:63], v[150:153], v[198:201], v[60:63]
	v_mfma_f32_16x16x32_bf16 v[56:59], v[158:161], v[198:201], v[56:59]
	v_mfma_f32_16x16x32_bf16 v[44:47], v[150:153], v[206:209], v[44:47]
	v_mfma_f32_16x16x32_bf16 v[40:43], v[158:161], v[206:209], v[40:43]
	v_mfma_f32_16x16x32_bf16 v[28:31], v[150:153], v[214:217], v[28:31]
	v_mfma_f32_16x16x32_bf16 v[24:27], v[158:161], v[214:217], v[24:27]
	v_mfma_f32_16x16x32_bf16 v[12:15], v[150:153], v[230:233], v[12:15]
	v_mfma_f32_16x16x32_bf16 v[8:11], v[158:161], v[230:233], v[8:11]
	s_setprio 0
	s_setprio 1
	v_mfma_f32_16x16x32_bf16 v[52:55], v[172:175], v[188:191], 0
	v_mfma_f32_16x16x32_bf16 v[48:51], v[180:183], v[188:191], 0
	v_mfma_f32_16x16x32_bf16 v[36:39], v[172:175], v[202:205], 0
	v_mfma_f32_16x16x32_bf16 v[32:35], v[180:183], v[202:205], 0
	v_mfma_f32_16x16x32_bf16 v[20:23], v[172:175], v[210:213], 0
	v_mfma_f32_16x16x32_bf16 v[16:19], v[180:183], v[210:213], 0
	v_mfma_f32_16x16x32_bf16 v[4:7], v[172:175], v[218:221], 0
	v_mfma_f32_16x16x32_bf16 v[0:3], v[180:183], v[218:221], 0
	v_mfma_f32_16x16x32_bf16 v[52:55], v[176:179], v[198:201], v[52:55]
	v_mfma_f32_16x16x32_bf16 v[48:51], v[184:187], v[198:201], v[48:51]
	v_mfma_f32_16x16x32_bf16 v[36:39], v[176:179], v[206:209], v[36:39]
	v_mfma_f32_16x16x32_bf16 v[32:35], v[184:187], v[206:209], v[32:35]
	v_mfma_f32_16x16x32_bf16 v[20:23], v[176:179], v[214:217], v[20:23]
	v_mfma_f32_16x16x32_bf16 v[16:19], v[184:187], v[214:217], v[16:19]
	v_mfma_f32_16x16x32_bf16 v[4:7], v[176:179], v[230:233], v[4:7]
	v_mfma_f32_16x16x32_bf16 v[0:3], v[184:187], v[230:233], v[0:3]
	s_setprio 0
	s_barrier
	s_add_i32 s63, 0, 0x18000
	v_add_u32_e32 v145, s63, v166
	s_add_i32 s78, 0, 0x1c000
	ds_read_b128 v[146:149], v145
	ds_read_b128 v[150:153], v145 offset:1024
	ds_read_b128 v[154:157], v145 offset:2048
	ds_read_b128 v[158:161], v145 offset:3072
	v_add_u32_e32 v145, s78, v166
	ds_read_b128 v[172:175], v145
	ds_read_b128 v[176:179], v145 offset:1024
	ds_read_b128 v[180:183], v145 offset:2048
	ds_read_b128 v[184:187], v145 offset:3072
	s_add_u32 s70, s70, 0x40000
	s_addc_u32 s71, s71, 0
	s_mov_b32 m0, s82
	v_lshl_add_u64 v[240:241], s[70:71], 0, v[138:139]
	ds_read_b128 v[188:191], v171 offset:32768
	ds_read_b128 v[198:201], v171 offset:33792
	ds_read_b128 v[202:205], v171 offset:34816
	ds_read_b128 v[206:209], v171 offset:35840
	ds_read_b128 v[210:213], v171 offset:36864
	ds_read_b128 v[214:217], v171 offset:37888
	ds_read_b128 v[218:221], v171 offset:38912
	ds_read_b128 v[230:233], v171 offset:39936
	global_load_lds_dwordx4 v[240:241], off
	v_lshl_add_u64 v[240:241], s[70:71], 0, v[136:137]
	s_mov_b32 m0, s83
	s_nop 0
	global_load_lds_dwordx4 v[240:241], off
	s_waitcnt vmcnt(8)
	s_waitcnt lgkmcnt(0)
	s_barrier
	s_setprio 1
	s_waitcnt lgkmcnt(0)
	v_mfma_f32_16x16x32_bf16 v[128:131], v[146:149], v[188:191], v[128:131]
	v_mfma_f32_16x16x32_bf16 v[124:127], v[154:157], v[188:191], v[124:127]
	v_mfma_f32_16x16x32_bf16 v[108:111], v[146:149], v[202:205], v[108:111]
	v_mfma_f32_16x16x32_bf16 v[104:107], v[154:157], v[202:205], v[104:107]
	v_mfma_f32_16x16x32_bf16 v[92:95], v[146:149], v[210:213], v[92:95]
	v_mfma_f32_16x16x32_bf16 v[88:91], v[154:157], v[210:213], v[88:91]
	v_mfma_f32_16x16x32_bf16 v[76:79], v[146:149], v[218:221], v[76:79]
	v_mfma_f32_16x16x32_bf16 v[72:75], v[154:157], v[218:221], v[72:75]
	v_mfma_f32_16x16x32_bf16 v[128:131], v[150:153], v[198:201], v[128:131]
	v_mfma_f32_16x16x32_bf16 v[124:127], v[158:161], v[198:201], v[124:127]
	v_mfma_f32_16x16x32_bf16 v[108:111], v[150:153], v[206:209], v[108:111]
	v_mfma_f32_16x16x32_bf16 v[104:107], v[158:161], v[206:209], v[104:107]
	v_mfma_f32_16x16x32_bf16 v[92:95], v[150:153], v[214:217], v[92:95]
	v_mfma_f32_16x16x32_bf16 v[88:91], v[158:161], v[214:217], v[88:91]
	v_mfma_f32_16x16x32_bf16 v[76:79], v[150:153], v[230:233], v[76:79]
	v_mfma_f32_16x16x32_bf16 v[72:75], v[158:161], v[230:233], v[72:75]
	s_setprio 0
	s_setprio 1
	v_mfma_f32_16x16x32_bf16 v[120:123], v[172:175], v[188:191], v[120:123]
	v_mfma_f32_16x16x32_bf16 v[116:119], v[180:183], v[188:191], v[116:119]
	v_mfma_f32_16x16x32_bf16 v[100:103], v[172:175], v[202:205], v[100:103]
	v_mfma_f32_16x16x32_bf16 v[96:99], v[180:183], v[202:205], v[96:99]
	v_mfma_f32_16x16x32_bf16 v[84:87], v[172:175], v[210:213], v[84:87]
	v_mfma_f32_16x16x32_bf16 v[80:83], v[180:183], v[210:213], v[80:83]
	v_mfma_f32_16x16x32_bf16 v[68:71], v[172:175], v[218:221], v[68:71]
	v_mfma_f32_16x16x32_bf16 v[64:67], v[180:183], v[218:221], v[64:67]
	v_mfma_f32_16x16x32_bf16 v[120:123], v[176:179], v[198:201], v[120:123]
	v_mfma_f32_16x16x32_bf16 v[116:119], v[184:187], v[198:201], v[116:119]
	v_mfma_f32_16x16x32_bf16 v[100:103], v[176:179], v[206:209], v[100:103]
	v_mfma_f32_16x16x32_bf16 v[96:99], v[184:187], v[206:209], v[96:99]
	v_mfma_f32_16x16x32_bf16 v[84:87], v[176:179], v[214:217], v[84:87]
	v_mfma_f32_16x16x32_bf16 v[80:83], v[184:187], v[214:217], v[80:83]
	v_mfma_f32_16x16x32_bf16 v[68:71], v[176:179], v[230:233], v[68:71]
	v_mfma_f32_16x16x32_bf16 v[64:67], v[184:187], v[230:233], v[64:67]
	s_setprio 0
	s_barrier
; #define PG8_STAGE(bufoff, gbase, voff) do { _Pragma("unroll") for (int _i = 0; _i < 2; ++_i) \
;         __builtin_amdgcn_global_load_lds((const unsigned*)((const char*)(gbase) + (voff)[_i]), (LAS unsigned*)(lds + (bufoff) + ldsw + _i * 8192), 16, 0, 0); } while (0)
; #define PG8_LDA(dst, b, h) do { _Pragma("unroll") for (int m = 0; m < 4; ++m) _Pragma("unroll") for (int k = 0; k < 2; ++k) dst[m][k] = *(const LAS bf16x8*)(lds + PG8_SA(b, h) + aoff + m * 2048 + k * 1024); } while (0)
; #define PG8_MMA(ai, bj, At, Bt) do { __builtin_amdgcn_s_setprio(1); _Pragma("unroll") for (int m = 0; m < 4; ++m) _Pragma("unroll") for (int n = 0; n < 2; ++n) _Pragma("unroll") for (int k = 0; k < 2; ++k) \
;         acc[ai][bj][m][n] = __builtin_amdgcn_mfma_f32_16x16x32_bf16(Bt[n][k], At[m][k], acc[ai][bj][m][n], 0, 0, 0); __builtin_amdgcn_s_setprio(0); } while (0)
; #define PG8_WAIT_V(n) asm volatile("s_waitcnt vmcnt(" #n ")" ::: "memory")
; #define PG8_WAIT_L(n) asm volatile("s_waitcnt lgkmcnt(" #n ")" ::: "memory")
; #define PG8_BAR __builtin_amdgcn_s_barrier()
; #define PG8_SCHED __builtin_amdgcn_sched_barrier(0)
; template <class Epi, class Sched>
; __device__ __forceinline__ void gemm_phase(LAS unsigned char* lds, const Gemm g, const Sched& S, const Epi& E, const int tid) {
;     ...
;             PG8_LDA(At, 1, 1); PG8_STAGE(PG8_SB(1, 0), b3, voffB); PG8_STAGE(PG8_SB(1, 1), b3 + hstep, voffB); PG8_STAGE(PG8_SA(1, 0), a3, voffA);
;             PG8_WAIT_V(8); PG8_WAIT_L(0); PG8_BAR; PG8_MMA(1, 0, At, B0); PG8_MMA(1, 1, At, B1); PG8_BAR; PG8_SCHED;
	s_add_i32 s63, s63, s74
	v_lshl_add_u64 v[162:163], v[162:163], 0, s[68:69]
	s_mov_b32 m0, s63
	ds_read_b128 v[188:191], v171 offset:49152
	ds_read_b128 v[198:201], v171 offset:50176
	ds_read_b128 v[202:205], v171 offset:51200
	ds_read_b128 v[206:209], v171 offset:52224
	ds_read_b128 v[210:213], v171 offset:53248
	ds_read_b128 v[214:217], v171 offset:54272
	ds_read_b128 v[218:221], v171 offset:55296
	ds_read_b128 v[230:233], v171 offset:56320
	global_load_lds_dwordx4 v[162:163], off
	s_add_i32 m0, s63, 0x2000
	s_add_u32 s66, s66, 0x40080
	v_lshl_add_u64 v[162:163], v[234:235], 0, s[68:69]
	s_addc_u32 s67, s67, 0
	s_add_i32 s63, s78, s74
	global_load_lds_dwordx4 v[162:163], off
	v_lshl_add_u64 v[162:163], s[66:67], 0, v[192:193]
	s_mov_b32 m0, s63
	s_nop 0
	global_load_lds_dwordx4 v[162:163], off
	v_lshl_add_u64 v[162:163], s[66:67], 0, v[134:135]
	s_add_i32 m0, s63, 0x2000
	s_nop 0
	global_load_lds_dwordx4 v[162:163], off
	v_lshl_add_u64 v[162:163], v[236:237], 0, s[68:69]
	s_mov_b32 m0, s93
	s_nop 0
	global_load_lds_dwordx4 v[162:163], off
	v_lshl_add_u64 v[162:163], v[238:239], 0, s[68:69]
	s_mov_b32 m0, s94
	s_nop 0
	global_load_lds_dwordx4 v[162:163], off
	s_waitcnt vmcnt(8)
	s_waitcnt lgkmcnt(0)
	s_barrier
	s_setprio 1
	s_waitcnt lgkmcnt(0)
	v_mfma_f32_16x16x32_bf16 v[60:63], v[146:149], v[188:191], v[60:63]
	v_mfma_f32_16x16x32_bf16 v[56:59], v[154:157], v[188:191], v[56:59]
	v_mfma_f32_16x16x32_bf16 v[44:47], v[146:149], v[202:205], v[44:47]
	v_mfma_f32_16x16x32_bf16 v[40:43], v[154:157], v[202:205], v[40:43]
	v_mfma_f32_16x16x32_bf16 v[28:31], v[146:149], v[210:213], v[28:31]
	v_mfma_f32_16x16x32_bf16 v[24:27], v[154:157], v[210:213], v[24:27]
	v_mfma_f32_16x16x32_bf16 v[12:15], v[146:149], v[218:221], v[12:15]
	v_mfma_f32_16x16x32_bf16 v[8:11], v[154:157], v[218:221], v[8:11]
	v_mfma_f32_16x16x32_bf16 v[60:63], v[150:153], v[198:201], v[60:63]
	v_mfma_f32_16x16x32_bf16 v[56:59], v[158:161], v[198:201], v[56:59]
	v_mfma_f32_16x16x32_bf16 v[44:47], v[150:153], v[206:209], v[44:47]
	v_mfma_f32_16x16x32_bf16 v[40:43], v[158:161], v[206:209], v[40:43]
	v_mfma_f32_16x16x32_bf16 v[28:31], v[150:153], v[214:217], v[28:31]
	v_mfma_f32_16x16x32_bf16 v[24:27], v[158:161], v[214:217], v[24:27]
	v_mfma_f32_16x16x32_bf16 v[12:15], v[150:153], v[230:233], v[12:15]
	v_mfma_f32_16x16x32_bf16 v[8:11], v[158:161], v[230:233], v[8:11]
	s_setprio 0
	s_setprio 1
	v_mfma_f32_16x16x32_bf16 v[52:55], v[172:175], v[188:191], v[52:55]
	v_mfma_f32_16x16x32_bf16 v[48:51], v[180:183], v[188:191], v[48:51]
	v_mfma_f32_16x16x32_bf16 v[36:39], v[172:175], v[202:205], v[36:39]
	v_mfma_f32_16x16x32_bf16 v[32:35], v[180:183], v[202:205], v[32:35]
	v_mfma_f32_16x16x32_bf16 v[20:23], v[172:175], v[210:213], v[20:23]
	v_mfma_f32_16x16x32_bf16 v[16:19], v[180:183], v[210:213], v[16:19]
	v_mfma_f32_16x16x32_bf16 v[4:7], v[172:175], v[218:221], v[4:7]
	v_mfma_f32_16x16x32_bf16 v[0:3], v[180:183], v[218:221], v[0:3]
	v_mfma_f32_16x16x32_bf16 v[52:55], v[176:179], v[198:201], v[52:55]
	v_mfma_f32_16x16x32_bf16 v[48:51], v[184:187], v[198:201], v[48:51]
	v_mfma_f32_16x16x32_bf16 v[36:39], v[176:179], v[206:209], v[36:39]
	v_mfma_f32_16x16x32_bf16 v[32:35], v[184:187], v[206:209], v[32:35]
	v_mfma_f32_16x16x32_bf16 v[20:23], v[176:179], v[214:217], v[20:23]
	v_mfma_f32_16x16x32_bf16 v[16:19], v[184:187], v[214:217], v[16:19]
	v_mfma_f32_16x16x32_bf16 v[4:7], v[176:179], v[230:233], v[4:7]
	v_mfma_f32_16x16x32_bf16 v[0:3], v[184:187], v[230:233], v[0:3]
	s_setprio 0
	s_barrier
	s_add_i32 s61, s61, 2
	s_add_u32 s64, s64, 0x100
	s_addc_u32 s65, s65, 0
	s_add_u32 s59, s59, 0x100
	s_addc_u32 s60, s60, 0
	s_cmp_gt_u32 s61, 13

; #define LAS __attribute__((address_space(3)))
; __device__ __forceinline__ unsigned cvtpk(float lo, float hi) { f32x2_t v = {lo, hi}; bf16x2_t b = __builtin_convertvector(v, bf16x2_t); return __builtin_bit_cast(unsigned, b); }
; __device__ __forceinline__ float silu2(float g2, float u2) { return (g2 * u2) * __builtin_amdgcn_rcpf(1.0f + __builtin_amdgcn_exp2f(g2)); }
; __device__ __forceinline__ void prenorm_commit(const PreNorm& p, LAS float* scr, int tid) {
;     if (tid < 256) { scr[tid] = rsqrtf(((p.st[0] + p.st[1]) + (p.st[2] + p.st[3])) * (1.0f / DM) + EPS); scr[256 + tid] = p.sw; }
;     asm volatile("s_waitcnt lgkmcnt(0)" ::: "memory"); __builtin_amdgcn_s_barrier(); asm volatile("" ::: "memory");
; }
;     __device__ __forceinline__ void operator()(const f32x4 (&acc)[2][2][4][2], const Unit& u, int wr, int wc, int fr, int fq, int tid, const Pre& pre) const {
;         prenorm_commit(pre, scr, tid);
;         const int row0 = u.pm * BM + wr * 64 + fr; const int col0 = u.pn * HALF + wc * 32 + 8 * fq;
;         const LAS float* sp = scr + 256 + wc * 32 + 8 * fq;
;         const f32x4 sg0 = *(const LAS f32x4*)sp * (-LOG2E), sg1 = *(const LAS f32x4*)(sp + 4) * (-LOG2E), su0 = *(const LAS f32x4*)(sp + HALF) * (-1.0f / LOG2E), su1 = *(const LAS f32x4*)(sp + HALF + 4) * (-1.0f / LOG2E);
; #pragma unroll
;         for (int ai = 0; ai < 2; ++ai)
; #pragma unroll
;             for (int m = 0; m < 4; ++m) { bf16_t* rowp = O + (size_t)(row0 + ai * HALF + m * 16) * FF + col0;
;                 const float rs = scr[ai * HALF + wr * 64 + m * 16 + fr]; const float rsg = rs * (-LOG2E), rsu = rs * (-1.0f / LOG2E);
;                 const f32x4 g0 = acc[ai][0][m][0] * rsg + sg0, g1 = acc[ai][0][m][1] * rsg + sg1, u0 = acc[ai][1][m][0] * rsu + su0, u1 = acc[ai][1][m][1] * rsu + su1;
;                 u32x4 w; w.x = cvtpk(silu2(g0[0], u0[0]), silu2(g0[1], u0[1])); w.y = cvtpk(silu2(g0[2], u0[2]), silu2(g0[3], u0[3]));
;                 w.z = cvtpk(silu2(g1[0], u1[0]), silu2(g1[1], u1[1])); w.w = cvtpk(silu2(g1[2], u1[2]), silu2(g1[3], u1[3]));
;                 *(u32x4*)rowp = w; }
.LBB0_171:
	s_and_saveexec_b64 s[64:65], s[4:5]
	s_cbranch_execz .LBB0_173
	s_waitcnt vmcnt(8)
	v_mov_b32_e32 v146, v113
	v_mov_b32_e32 v147, v114
	v_mov_b32_e32 v113, v115
	v_pk_add_f32 v[112:113], v[146:147], v[112:113]
	s_nop 0
	v_add_f32_e32 v112, v112, v113
	v_fmamk_f32 v112, v112, 0x3a800000, v222
	v_mul_f32_e32 v113, 0x4b800000, v112
	v_cmp_gt_f32_e32 vcc, s45, v112
	s_nop 1
	v_cndmask_b32_e32 v112, v112, v113, vcc
	v_rsq_f32_e32 v112, v112
	s_nop 0
	v_mul_f32_e32 v113, 0x45800000, v112
	v_cndmask_b32_e32 v112, v112, v113, vcc
	ds_write2st64_b32 v164, v112, v144 offset1:4
.LBB0_173:
	s_or_b64 exec, exec, s[64:65]
	s_waitcnt lgkmcnt(0)
	s_barrier
	s_nop 0
	ds_read_b128 v[112:115], v167
	ds_read_b128 v[148:151], v167 offset:16
	ds_read2_b32 v[162:163], v168 offset1:16
	v_lshl_or_b32 v158, s53, 7, v170
	ds_read_b128 v[154:157], v167 offset:528
	s_waitcnt lgkmcnt(3)
	v_pk_mul_f32 v[146:147], v[112:113], s[44:45] op_sel_hi:[1,0]
	s_waitcnt lgkmcnt(2)
	v_pk_mul_f32 v[112:113], v[150:151], s[44:45] op_sel_hi:[1,0]
	ds_read_b128 v[150:153], v167 offset:512
	s_waitcnt lgkmcnt(2)
	v_mul_f32_e32 v174, 0xbfb8aa3b, v162
	v_pk_mul_f32 v[144:145], v[114:115], s[44:45] op_sel_hi:[1,0]
	v_pk_mul_f32 v[114:115], v[148:149], s[44:45] op_sel_hi:[1,0]
	s_waitcnt lgkmcnt(1)
	v_pk_mul_f32 v[154:155], v[154:155], s[36:37] op_sel_hi:[1,0]
	v_mul_f32_e32 v162, 0xbf317218, v162
	v_pk_fma_f32 v[128:129], v[128:129], v[174:175], v[146:147] op_sel_hi:[1,0,1] neg_lo:[0,0,1] neg_hi:[0,0,1]
	v_pk_fma_f32 v[130:131], v[130:131], v[174:175], v[144:145] op_sel_hi:[1,0,1] neg_lo:[0,0,1] neg_hi:[0,0,1]
	v_pk_fma_f32 v[126:127], v[126:127], v[174:175], v[112:113] op_sel_hi:[1,0,1] neg_lo:[0,0,1] neg_hi:[0,0,1]
	v_pk_fma_f32 v[124:125], v[124:125], v[174:175], v[114:115] op_sel_hi:[1,0,1] neg_lo:[0,0,1] neg_hi:[0,0,1]
	v_pk_fma_f32 v[174:175], v[116:117], v[162:163], v[154:155] op_sel_hi:[1,0,1] neg_lo:[0,0,1] neg_hi:[0,0,1]
	v_exp_f32_e32 v116, v128
	v_exp_f32_e32 v117, v129
	s_waitcnt lgkmcnt(0)
	v_pk_mul_f32 v[150:151], v[150:151], s[36:37] op_sel_hi:[1,0]
	v_pk_mul_f32 v[148:149], v[152:153], s[36:37] op_sel_hi:[1,0]
	v_add_f32_e32 v116, 1.0, v116
	v_add_f32_e32 v117, 1.0, v117
	v_rcp_f32_e32 v116, v116
	v_rcp_f32_e32 v117, v117
	v_pk_fma_f32 v[120:121], v[120:121], v[162:163], v[150:151] op_sel_hi:[1,0,1] neg_lo:[0,0,1] neg_hi:[0,0,1]
	v_pk_fma_f32 v[122:123], v[122:123], v[162:163], v[148:149] op_sel_hi:[1,0,1] neg_lo:[0,0,1] neg_hi:[0,0,1]
	v_pk_mul_f32 v[120:121], v[128:129], v[120:121]
	v_pk_mul_f32 v[122:123], v[130:131], v[122:123]
	v_pk_mul_f32 v[116:117], v[120:121], v[116:117]
	v_pk_mul_f32 v[152:153], v[156:157], s[36:37] op_sel_hi:[1,0]
	v_cvt_pk_bf16_f32 v116, v116, v117
	v_exp_f32_e32 v117, v130
	v_pk_fma_f32 v[118:119], v[118:119], v[162:163], v[152:153] op_sel_hi:[1,0,1] neg_lo:[0,0,1] neg_hi:[0,0,1]
	v_lshl_add_u32 v172, s52, 8, v165
	v_ashrrev_i32_e32 v159, 31, v158
	v_add_f32_e32 v117, 1.0, v117
	v_rcp_f32_e32 v120, v117
	v_exp_f32_e32 v117, v131
	v_mov_b64_e32 v[156:157], s[16:17]
	v_mad_i64_i32 v[160:161], s[52:53], v172, s31, v[156:157]
	v_add_f32_e32 v117, 1.0, v117
	v_rcp_f32_e32 v121, v117
	v_lshlrev_b64 v[158:159], 1, v[158:159]
	v_lshl_add_u64 v[160:161], v[160:161], 0, v[158:159]
	s_mov_b64 s[64:65], -1
	v_pk_mul_f32 v[120:121], v[122:123], v[120:121]
	v_pk_mul_f32 v[122:123], v[126:127], v[118:119]
	v_cvt_pk_bf16_f32 v117, v120, v121
	v_exp_f32_e32 v120, v124
	v_exp_f32_e32 v121, v125
	v_pk_mul_f32 v[118:119], v[124:125], v[174:175]
	s_andn2_b64 vcc, exec, s[6:7]
	v_add_f32_e32 v120, 1.0, v120
	v_add_f32_e32 v121, 1.0, v121
	v_rcp_f32_e32 v120, v120
	v_rcp_f32_e32 v121, v121
	s_nop 0
	v_pk_mul_f32 v[118:119], v[118:119], v[120:121]
	s_nop 0
	v_cvt_pk_bf16_f32 v118, v118, v119
	v_exp_f32_e32 v119, v126
	s_nop 0
	v_add_f32_e32 v119, 1.0, v119
	v_rcp_f32_e32 v120, v119
	v_exp_f32_e32 v119, v127
	s_nop 0
	v_add_f32_e32 v119, 1.0, v119
	v_rcp_f32_e32 v121, v119
	s_nop 0
	v_pk_mul_f32 v[120:121], v[122:123], v[120:121]
	s_nop 0
	v_cvt_pk_bf16_f32 v119, v120, v121
	global_store_dwordx4 v[160:161], v[116:119], off
	v_mul_f32_e32 v120, 0xbf317218, v163
	v_pk_fma_f32 v[100:101], v[100:101], v[120:121], v[150:151] op_sel_hi:[1,0,1] neg_lo:[0,0,1] neg_hi:[0,0,1]
	v_mul_f32_e32 v118, 0xbfb8aa3b, v163
	v_pk_fma_f32 v[108:109], v[108:109], v[118:119], v[146:147] op_sel_hi:[1,0,1] neg_lo:[0,0,1] neg_hi:[0,0,1]
	v_pk_fma_f32 v[110:111], v[110:111], v[118:119], v[144:145] op_sel_hi:[1,0,1] neg_lo:[0,0,1] neg_hi:[0,0,1]
	v_pk_fma_f32 v[106:107], v[106:107], v[118:119], v[112:113] op_sel_hi:[1,0,1] neg_lo:[0,0,1] neg_hi:[0,0,1]
	v_pk_fma_f32 v[104:105], v[104:105], v[118:119], v[114:115] op_sel_hi:[1,0,1] neg_lo:[0,0,1] neg_hi:[0,0,1]
	v_pk_fma_f32 v[118:119], v[96:97], v[120:121], v[154:155] op_sel_hi:[1,0,1] neg_lo:[0,0,1] neg_hi:[0,0,1]
	v_exp_f32_e32 v96, v108
	v_exp_f32_e32 v97, v109
	v_pk_mul_f32 v[100:101], v[108:109], v[100:101]
	v_pk_fma_f32 v[102:103], v[102:103], v[120:121], v[148:149] op_sel_hi:[1,0,1] neg_lo:[0,0,1] neg_hi:[0,0,1]
	v_add_f32_e32 v96, 1.0, v96
	v_add_f32_e32 v97, 1.0, v97
	v_rcp_f32_e32 v96, v96
	v_rcp_f32_e32 v97, v97
	v_pk_mul_f32 v[102:103], v[110:111], v[102:103]
	v_pk_fma_f32 v[98:99], v[98:99], v[120:121], v[152:153] op_sel_hi:[1,0,1] neg_lo:[0,0,1] neg_hi:[0,0,1]
	v_or_b32_e32 v116, 16, v172
	v_pk_mul_f32 v[96:97], v[100:101], v[96:97]
	v_mad_i64_i32 v[116:117], s[52:53], v116, s31, v[156:157]
	v_cvt_pk_bf16_f32 v96, v96, v97
	v_exp_f32_e32 v97, v110
	v_lshl_add_u64 v[116:117], v[116:117], 0, v[158:159]
	v_add_f32_e32 v97, 1.0, v97
	v_rcp_f32_e32 v100, v97
	v_exp_f32_e32 v97, v111
	s_nop 0
	v_add_f32_e32 v97, 1.0, v97
	v_rcp_f32_e32 v101, v97
	s_nop 0
	v_pk_mul_f32 v[100:101], v[102:103], v[100:101]
	s_nop 0
	v_cvt_pk_bf16_f32 v97, v100, v101
	v_exp_f32_e32 v100, v104
	v_exp_f32_e32 v101, v105
	v_pk_mul_f32 v[102:103], v[106:107], v[98:99]
	v_pk_mul_f32 v[98:99], v[104:105], v[118:119]
	v_add_f32_e32 v100, 1.0, v100
	v_add_f32_e32 v101, 1.0, v101
	v_rcp_f32_e32 v100, v100
	v_rcp_f32_e32 v101, v101
	s_nop 0
	v_pk_mul_f32 v[98:99], v[98:99], v[100:101]
	s_nop 0
	v_cvt_pk_bf16_f32 v98, v98, v99
	v_exp_f32_e32 v99, v106
	s_nop 0
	v_add_f32_e32 v99, 1.0, v99
	v_rcp_f32_e32 v100, v99
	v_exp_f32_e32 v99, v107
	s_nop 0
	v_add_f32_e32 v99, 1.0, v99
	v_rcp_f32_e32 v101, v99
	s_nop 0
	v_pk_mul_f32 v[100:101], v[102:103], v[100:101]
	s_nop 0
	v_cvt_pk_bf16_f32 v99, v100, v101
	global_store_dwordx4 v[116:117], v[96:99], off
	ds_read2_b32 v[98:99], v168 offset0:32 offset1:48
	s_waitcnt lgkmcnt(0)
; __device__ __forceinline__ unsigned cvtpk(float lo, float hi) { f32x2_t v = {lo, hi}; bf16x2_t b = __builtin_convertvector(v, bf16x2_t); return __builtin_bit_cast(unsigned, b); }
; __device__ __forceinline__ float silu2(float g2, float u2) { return (g2 * u2) * __builtin_amdgcn_rcpf(1.0f + __builtin_amdgcn_exp2f(g2)); }
;     __device__ __forceinline__ void operator()(const f32x4 (&acc)[2][2][4][2], const Unit& u, int wr, int wc, int fr, int fq, int tid, const Pre& pre) const {
;     ...
;         for (int ai = 0; ai < 2; ++ai)
; #pragma unroll
;             for (int m = 0; m < 4; ++m) { bf16_t* rowp = O + (size_t)(row0 + ai * HALF + m * 16) * FF + col0;
;                 const float rs = scr[ai * HALF + wr * 64 + m * 16 + fr]; const float rsg = rs * (-LOG2E), rsu = rs * (-1.0f / LOG2E);
;                 const f32x4 g0 = acc[ai][0][m][0] * rsg + sg0, g1 = acc[ai][0][m][1] * rsg + sg1, u0 = acc[ai][1][m][0] * rsu + su0, u1 = acc[ai][1][m][1] * rsu + su1;
;                 u32x4 w; w.x = cvtpk(silu2(g0[0], u0[0]), silu2(g0[1], u0[1])); w.y = cvtpk(silu2(g0[2], u0[2]), silu2(g0[3], u0[3]));
;                 w.z = cvtpk(silu2(g1[0], u1[0]), silu2(g1[1], u1[1])); w.w = cvtpk(silu2(g1[2], u1[2]), silu2(g1[3], u1[3]));
;                 *(u32x4*)rowp = w; }
	v_mul_f32_e32 v100, 0xbfb8aa3b, v98
	v_mul_f32_e32 v98, 0xbf317218, v98
	v_pk_fma_f32 v[92:93], v[92:93], v[100:101], v[146:147] op_sel_hi:[1,0,1] neg_lo:[0,0,1] neg_hi:[0,0,1]
	v_pk_fma_f32 v[94:95], v[94:95], v[100:101], v[144:145] op_sel_hi:[1,0,1] neg_lo:[0,0,1] neg_hi:[0,0,1]
	v_pk_fma_f32 v[90:91], v[90:91], v[100:101], v[112:113] op_sel_hi:[1,0,1] neg_lo:[0,0,1] neg_hi:[0,0,1]
	v_pk_fma_f32 v[88:89], v[88:89], v[100:101], v[114:115] op_sel_hi:[1,0,1] neg_lo:[0,0,1] neg_hi:[0,0,1]
	v_pk_fma_f32 v[100:101], v[80:81], v[98:99], v[154:155] op_sel_hi:[1,0,1] neg_lo:[0,0,1] neg_hi:[0,0,1]
	v_exp_f32_e32 v80, v92
	v_exp_f32_e32 v81, v93
	v_pk_fma_f32 v[84:85], v[84:85], v[98:99], v[150:151] op_sel_hi:[1,0,1] neg_lo:[0,0,1] neg_hi:[0,0,1]
	v_pk_fma_f32 v[86:87], v[86:87], v[98:99], v[148:149] op_sel_hi:[1,0,1] neg_lo:[0,0,1] neg_hi:[0,0,1]
	v_add_f32_e32 v80, 1.0, v80
	v_add_f32_e32 v81, 1.0, v81
	v_rcp_f32_e32 v80, v80
	v_rcp_f32_e32 v81, v81
	v_pk_mul_f32 v[84:85], v[92:93], v[84:85]
	v_pk_mul_f32 v[86:87], v[94:95], v[86:87]
	v_pk_fma_f32 v[82:83], v[82:83], v[98:99], v[152:153] op_sel_hi:[1,0,1] neg_lo:[0,0,1] neg_hi:[0,0,1]
	v_pk_mul_f32 v[80:81], v[84:85], v[80:81]
	v_or_b32_e32 v96, 32, v172
	v_cvt_pk_bf16_f32 v80, v80, v81
	v_exp_f32_e32 v81, v94
	v_mad_i64_i32 v[96:97], s[52:53], v96, s31, v[156:157]
	v_lshl_add_u64 v[96:97], v[96:97], 0, v[158:159]
	v_add_f32_e32 v81, 1.0, v81
	v_rcp_f32_e32 v84, v81
	v_exp_f32_e32 v81, v95
	s_nop 0
	v_add_f32_e32 v81, 1.0, v81
	v_rcp_f32_e32 v85, v81
	s_nop 0
	v_pk_mul_f32 v[84:85], v[86:87], v[84:85]
	s_nop 0
	v_cvt_pk_bf16_f32 v81, v84, v85
	v_exp_f32_e32 v84, v88
	v_exp_f32_e32 v85, v89
	v_pk_mul_f32 v[86:87], v[90:91], v[82:83]
	v_pk_mul_f32 v[82:83], v[88:89], v[100:101]
	v_add_f32_e32 v84, 1.0, v84
	v_add_f32_e32 v85, 1.0, v85
	v_rcp_f32_e32 v84, v84
	v_rcp_f32_e32 v85, v85
	s_nop 0
	v_pk_mul_f32 v[82:83], v[82:83], v[84:85]
	s_nop 0
	v_cvt_pk_bf16_f32 v82, v82, v83
	v_exp_f32_e32 v83, v90
	s_nop 0
	v_add_f32_e32 v83, 1.0, v83
	v_rcp_f32_e32 v84, v83
	v_exp_f32_e32 v83, v91
	s_nop 0
	v_add_f32_e32 v83, 1.0, v83
	v_rcp_f32_e32 v85, v83
	s_nop 0
	v_pk_mul_f32 v[84:85], v[86:87], v[84:85]
	s_nop 0
	v_cvt_pk_bf16_f32 v83, v84, v85
	global_store_dwordx4 v[96:97], v[80:83], off
	v_mul_f32_e32 v84, 0xbf317218, v99
	v_pk_fma_f32 v[68:69], v[68:69], v[84:85], v[150:151] op_sel_hi:[1,0,1] neg_lo:[0,0,1] neg_hi:[0,0,1]
	v_mul_f32_e32 v82, 0xbfb8aa3b, v99
	v_pk_fma_f32 v[76:77], v[76:77], v[82:83], v[146:147] op_sel_hi:[1,0,1] neg_lo:[0,0,1] neg_hi:[0,0,1]
	v_pk_fma_f32 v[78:79], v[78:79], v[82:83], v[144:145] op_sel_hi:[1,0,1] neg_lo:[0,0,1] neg_hi:[0,0,1]
	v_pk_fma_f32 v[74:75], v[74:75], v[82:83], v[112:113] op_sel_hi:[1,0,1] neg_lo:[0,0,1] neg_hi:[0,0,1]
	v_pk_fma_f32 v[72:73], v[72:73], v[82:83], v[114:115] op_sel_hi:[1,0,1] neg_lo:[0,0,1] neg_hi:[0,0,1]
	v_pk_fma_f32 v[82:83], v[64:65], v[84:85], v[154:155] op_sel_hi:[1,0,1] neg_lo:[0,0,1] neg_hi:[0,0,1]
	v_exp_f32_e32 v64, v76
	v_exp_f32_e32 v65, v77
	v_pk_mul_f32 v[68:69], v[76:77], v[68:69]
	v_pk_fma_f32 v[70:71], v[70:71], v[84:85], v[148:149] op_sel_hi:[1,0,1] neg_lo:[0,0,1] neg_hi:[0,0,1]
	v_add_f32_e32 v64, 1.0, v64
	v_add_f32_e32 v65, 1.0, v65
	v_rcp_f32_e32 v64, v64
	v_rcp_f32_e32 v65, v65
	v_pk_mul_f32 v[70:71], v[78:79], v[70:71]
	v_pk_fma_f32 v[66:67], v[66:67], v[84:85], v[152:153] op_sel_hi:[1,0,1] neg_lo:[0,0,1] neg_hi:[0,0,1]
	v_or_b32_e32 v80, 48, v172
	v_pk_mul_f32 v[64:65], v[68:69], v[64:65]
	v_mad_i64_i32 v[80:81], s[52:53], v80, s31, v[156:157]
	v_cvt_pk_bf16_f32 v64, v64, v65
	v_exp_f32_e32 v65, v78
	v_lshl_add_u64 v[80:81], v[80:81], 0, v[158:159]
	v_add_f32_e32 v65, 1.0, v65
	v_rcp_f32_e32 v68, v65
	v_exp_f32_e32 v65, v79
	s_nop 0
	v_add_f32_e32 v65, 1.0, v65
	v_rcp_f32_e32 v69, v65
	s_nop 0
	v_pk_mul_f32 v[68:69], v[70:71], v[68:69]
	s_nop 0
	v_cvt_pk_bf16_f32 v65, v68, v69
	v_exp_f32_e32 v68, v72
	v_exp_f32_e32 v69, v73
	v_pk_mul_f32 v[70:71], v[74:75], v[66:67]
	v_pk_mul_f32 v[66:67], v[72:73], v[82:83]
	v_add_f32_e32 v68, 1.0, v68
	v_add_f32_e32 v69, 1.0, v69
	v_rcp_f32_e32 v68, v68
	v_rcp_f32_e32 v69, v69
	s_nop 0
	v_pk_mul_f32 v[66:67], v[66:67], v[68:69]
	s_nop 0
	v_cvt_pk_bf16_f32 v66, v66, v67
	v_exp_f32_e32 v67, v74
	s_nop 0
	v_add_f32_e32 v67, 1.0, v67
	v_rcp_f32_e32 v68, v67
	v_exp_f32_e32 v67, v75
	s_nop 0
	v_add_f32_e32 v67, 1.0, v67
	v_rcp_f32_e32 v69, v67
	s_nop 0
	v_pk_mul_f32 v[68:69], v[70:71], v[68:69]
	s_nop 0
	v_cvt_pk_bf16_f32 v67, v68, v69
	global_store_dwordx4 v[80:81], v[64:67], off
	ds_read_b32 v67, v169
	s_waitcnt lgkmcnt(0)
; __device__ __forceinline__ unsigned cvtpk(float lo, float hi) { f32x2_t v = {lo, hi}; bf16x2_t b = __builtin_convertvector(v, bf16x2_t); return __builtin_bit_cast(unsigned, b); }
; __device__ __forceinline__ float silu2(float g2, float u2) { return (g2 * u2) * __builtin_amdgcn_rcpf(1.0f + __builtin_amdgcn_exp2f(g2)); }
;     __device__ __forceinline__ void operator()(const f32x4 (&acc)[2][2][4][2], const Unit& u, int wr, int wc, int fr, int fq, int tid, const Pre& pre) const {
;     ...
;         for (int ai = 0; ai < 2; ++ai)
; #pragma unroll
;             for (int m = 0; m < 4; ++m) { bf16_t* rowp = O + (size_t)(row0 + ai * HALF + m * 16) * FF + col0;
;                 const float rs = scr[ai * HALF + wr * 64 + m * 16 + fr]; const float rsg = rs * (-LOG2E), rsu = rs * (-1.0f / LOG2E);
;                 const f32x4 g0 = acc[ai][0][m][0] * rsg + sg0, g1 = acc[ai][0][m][1] * rsg + sg1, u0 = acc[ai][1][m][0] * rsu + su0, u1 = acc[ai][1][m][1] * rsu + su1;
;                 u32x4 w; w.x = cvtpk(silu2(g0[0], u0[0]), silu2(g0[1], u0[1])); w.y = cvtpk(silu2(g0[2], u0[2]), silu2(g0[3], u0[3]));
;                 w.z = cvtpk(silu2(g1[0], u1[0]), silu2(g1[1], u1[1])); w.w = cvtpk(silu2(g1[2], u1[2]), silu2(g1[3], u1[3]));
;                 *(u32x4*)rowp = w; }
	v_mul_f32_e32 v68, 0xbf317218, v67
	v_mul_f32_e32 v66, 0xbfb8aa3b, v67
	v_pk_fma_f32 v[60:61], v[60:61], v[66:67], v[146:147] op_sel_hi:[1,0,1] neg_lo:[0,0,1] neg_hi:[0,0,1]
	v_pk_fma_f32 v[62:63], v[62:63], v[66:67], v[144:145] op_sel_hi:[1,0,1] neg_lo:[0,0,1] neg_hi:[0,0,1]
	v_pk_fma_f32 v[58:59], v[58:59], v[66:67], v[112:113] op_sel_hi:[1,0,1] neg_lo:[0,0,1] neg_hi:[0,0,1]
	v_pk_fma_f32 v[56:57], v[56:57], v[66:67], v[114:115] op_sel_hi:[1,0,1] neg_lo:[0,0,1] neg_hi:[0,0,1]
	v_pk_fma_f32 v[66:67], v[48:49], v[68:69], v[154:155] op_sel_hi:[1,0,1] neg_lo:[0,0,1] neg_hi:[0,0,1]
	v_exp_f32_e32 v48, v60
	v_exp_f32_e32 v49, v61
	v_pk_fma_f32 v[52:53], v[52:53], v[68:69], v[150:151] op_sel_hi:[1,0,1] neg_lo:[0,0,1] neg_hi:[0,0,1]
	v_pk_fma_f32 v[54:55], v[54:55], v[68:69], v[148:149] op_sel_hi:[1,0,1] neg_lo:[0,0,1] neg_hi:[0,0,1]
	v_add_f32_e32 v48, 1.0, v48
	v_add_f32_e32 v49, 1.0, v49
	v_rcp_f32_e32 v48, v48
	v_rcp_f32_e32 v49, v49
	v_pk_mul_f32 v[52:53], v[60:61], v[52:53]
	v_pk_mul_f32 v[54:55], v[62:63], v[54:55]
	v_pk_fma_f32 v[50:51], v[50:51], v[68:69], v[152:153] op_sel_hi:[1,0,1] neg_lo:[0,0,1] neg_hi:[0,0,1]
	v_pk_mul_f32 v[48:49], v[52:53], v[48:49]
	v_add_u32_e32 v64, 0x80, v172
	v_cvt_pk_bf16_f32 v48, v48, v49
	v_exp_f32_e32 v49, v62
	v_mad_i64_i32 v[64:65], s[52:53], v64, s31, v[156:157]
	v_lshl_add_u64 v[64:65], v[64:65], 0, v[158:159]
	v_add_f32_e32 v49, 1.0, v49
	v_rcp_f32_e32 v52, v49
	v_exp_f32_e32 v49, v63
	s_nop 0
	v_add_f32_e32 v49, 1.0, v49
	v_rcp_f32_e32 v53, v49
	s_nop 0
	v_pk_mul_f32 v[52:53], v[54:55], v[52:53]
	s_nop 0
	v_cvt_pk_bf16_f32 v49, v52, v53
	v_exp_f32_e32 v52, v56
	v_exp_f32_e32 v53, v57
	v_pk_mul_f32 v[54:55], v[58:59], v[50:51]
	v_pk_mul_f32 v[50:51], v[56:57], v[66:67]
	v_add_f32_e32 v52, 1.0, v52
	v_add_f32_e32 v53, 1.0, v53
	v_rcp_f32_e32 v52, v52
	v_rcp_f32_e32 v53, v53
	s_nop 0
	v_pk_mul_f32 v[50:51], v[50:51], v[52:53]
	s_nop 0
	v_cvt_pk_bf16_f32 v50, v50, v51
	v_exp_f32_e32 v51, v58
	s_nop 0
	v_add_f32_e32 v51, 1.0, v51
	v_rcp_f32_e32 v52, v51
	v_exp_f32_e32 v51, v59
	s_nop 0
	v_add_f32_e32 v51, 1.0, v51
	v_rcp_f32_e32 v53, v51
	s_nop 0
	v_pk_mul_f32 v[52:53], v[54:55], v[52:53]
	s_nop 0
	v_cvt_pk_bf16_f32 v51, v52, v53
	global_store_dwordx4 v[64:65], v[48:51], off
	ds_read2_b32 v[50:51], v168 offset0:144 offset1:160
	s_waitcnt lgkmcnt(0)
; __device__ __forceinline__ unsigned cvtpk(float lo, float hi) { f32x2_t v = {lo, hi}; bf16x2_t b = __builtin_convertvector(v, bf16x2_t); return __builtin_bit_cast(unsigned, b); }
; __device__ __forceinline__ float silu2(float g2, float u2) { return (g2 * u2) * __builtin_amdgcn_rcpf(1.0f + __builtin_amdgcn_exp2f(g2)); }
; #define PG8_BAR __builtin_amdgcn_s_barrier()
;     __device__ __forceinline__ void operator()(const f32x4 (&acc)[2][2][4][2], const Unit& u, int wr, int wc, int fr, int fq, int tid, const Pre& pre) const {
;     ...
;         for (int ai = 0; ai < 2; ++ai)
; #pragma unroll
;             for (int m = 0; m < 4; ++m) { bf16_t* rowp = O + (size_t)(row0 + ai * HALF + m * 16) * FF + col0;
;                 const float rs = scr[ai * HALF + wr * 64 + m * 16 + fr]; const float rsg = rs * (-LOG2E), rsu = rs * (-1.0f / LOG2E);
;                 const f32x4 g0 = acc[ai][0][m][0] * rsg + sg0, g1 = acc[ai][0][m][1] * rsg + sg1, u0 = acc[ai][1][m][0] * rsu + su0, u1 = acc[ai][1][m][1] * rsu + su1;
;                 u32x4 w; w.x = cvtpk(silu2(g0[0], u0[0]), silu2(g0[1], u0[1])); w.y = cvtpk(silu2(g0[2], u0[2]), silu2(g0[3], u0[3]));
;                 w.z = cvtpk(silu2(g1[0], u1[0]), silu2(g1[1], u1[1])); w.w = cvtpk(silu2(g1[2], u1[2]), silu2(g1[3], u1[3]));
;                 *(u32x4*)rowp = w; }
; template <class Epi, class Sched>
; __device__ __forceinline__ void gemm_phase(LAS unsigned char* lds, const Gemm g, const Sched& S, const Epi& E, const int tid) {
;     ...
;         if (wr == 0) PG8_BAR;
;         E(acc, cur, wr, wc, fr, fq, tid, pre);
;         if (!has_next) break;
; #pragma unroll
;         for (int a = 0; a < 2; ++a)
; #pragma unroll
;             for (int b = 0; b < 2; ++b)
; #pragma unroll
;                 for (int m = 0; m < 4; ++m)
; #pragma unroll
;                     for (int n = 0; n < 2; ++n) acc[a][b][m][n] = (f32x4){0.f, 0.f, 0.f, 0.f};
;         cur = nxt; cA = nA; cB = nB; ++ui;
;         if (wr == 1) PG8_BAR;
;     }
	v_mul_f32_e32 v52, 0xbfb8aa3b, v50
	v_mul_f32_e32 v50, 0xbf317218, v50
	v_pk_fma_f32 v[44:45], v[44:45], v[52:53], v[146:147] op_sel_hi:[1,0,1] neg_lo:[0,0,1] neg_hi:[0,0,1]
	v_pk_fma_f32 v[46:47], v[46:47], v[52:53], v[144:145] op_sel_hi:[1,0,1] neg_lo:[0,0,1] neg_hi:[0,0,1]
	v_pk_fma_f32 v[42:43], v[42:43], v[52:53], v[112:113] op_sel_hi:[1,0,1] neg_lo:[0,0,1] neg_hi:[0,0,1]
	v_pk_fma_f32 v[40:41], v[40:41], v[52:53], v[114:115] op_sel_hi:[1,0,1] neg_lo:[0,0,1] neg_hi:[0,0,1]
	v_pk_fma_f32 v[52:53], v[32:33], v[50:51], v[154:155] op_sel_hi:[1,0,1] neg_lo:[0,0,1] neg_hi:[0,0,1]
	v_exp_f32_e32 v32, v44
	v_exp_f32_e32 v33, v45
	v_pk_fma_f32 v[36:37], v[36:37], v[50:51], v[150:151] op_sel_hi:[1,0,1] neg_lo:[0,0,1] neg_hi:[0,0,1]
	v_pk_fma_f32 v[38:39], v[38:39], v[50:51], v[148:149] op_sel_hi:[1,0,1] neg_lo:[0,0,1] neg_hi:[0,0,1]
	v_add_f32_e32 v32, 1.0, v32
	v_add_f32_e32 v33, 1.0, v33
	v_rcp_f32_e32 v32, v32
	v_rcp_f32_e32 v33, v33
	v_pk_mul_f32 v[36:37], v[44:45], v[36:37]
	v_pk_mul_f32 v[38:39], v[46:47], v[38:39]
	v_pk_fma_f32 v[34:35], v[34:35], v[50:51], v[152:153] op_sel_hi:[1,0,1] neg_lo:[0,0,1] neg_hi:[0,0,1]
	v_pk_mul_f32 v[32:33], v[36:37], v[32:33]
	v_add_u32_e32 v48, 0x90, v172
	v_cvt_pk_bf16_f32 v32, v32, v33
	v_exp_f32_e32 v33, v46
	v_mad_i64_i32 v[48:49], s[52:53], v48, s31, v[156:157]
	v_lshl_add_u64 v[48:49], v[48:49], 0, v[158:159]
	v_add_f32_e32 v33, 1.0, v33
	v_rcp_f32_e32 v36, v33
	v_exp_f32_e32 v33, v47
	s_nop 0
	v_add_f32_e32 v33, 1.0, v33
	v_rcp_f32_e32 v37, v33
	s_nop 0
	v_pk_mul_f32 v[36:37], v[38:39], v[36:37]
	s_nop 0
	v_cvt_pk_bf16_f32 v33, v36, v37
	v_exp_f32_e32 v36, v40
	v_exp_f32_e32 v37, v41
	v_pk_mul_f32 v[38:39], v[42:43], v[34:35]
	v_pk_mul_f32 v[34:35], v[40:41], v[52:53]
	v_add_f32_e32 v36, 1.0, v36
	v_add_f32_e32 v37, 1.0, v37
	v_rcp_f32_e32 v36, v36
	v_rcp_f32_e32 v37, v37
	s_nop 0
	v_pk_mul_f32 v[34:35], v[34:35], v[36:37]
	s_nop 0
	v_cvt_pk_bf16_f32 v34, v34, v35
	v_exp_f32_e32 v35, v42
	s_nop 0
	v_add_f32_e32 v35, 1.0, v35
	v_rcp_f32_e32 v36, v35
	v_exp_f32_e32 v35, v43
	s_nop 0
	v_add_f32_e32 v35, 1.0, v35
	v_rcp_f32_e32 v37, v35
	s_nop 0
	v_pk_mul_f32 v[36:37], v[38:39], v[36:37]
	s_nop 0
	v_cvt_pk_bf16_f32 v35, v36, v37
	global_store_dwordx4 v[48:49], v[32:35], off
	v_mul_f32_e32 v36, 0xbf317218, v51
	v_pk_fma_f32 v[20:21], v[20:21], v[36:37], v[150:151] op_sel_hi:[1,0,1] neg_lo:[0,0,1] neg_hi:[0,0,1]
	v_mul_f32_e32 v34, 0xbfb8aa3b, v51
	v_pk_fma_f32 v[28:29], v[28:29], v[34:35], v[146:147] op_sel_hi:[1,0,1] neg_lo:[0,0,1] neg_hi:[0,0,1]
	v_pk_fma_f32 v[30:31], v[30:31], v[34:35], v[144:145] op_sel_hi:[1,0,1] neg_lo:[0,0,1] neg_hi:[0,0,1]
	v_pk_fma_f32 v[26:27], v[26:27], v[34:35], v[112:113] op_sel_hi:[1,0,1] neg_lo:[0,0,1] neg_hi:[0,0,1]
	v_pk_fma_f32 v[24:25], v[24:25], v[34:35], v[114:115] op_sel_hi:[1,0,1] neg_lo:[0,0,1] neg_hi:[0,0,1]
	v_pk_fma_f32 v[34:35], v[16:17], v[36:37], v[154:155] op_sel_hi:[1,0,1] neg_lo:[0,0,1] neg_hi:[0,0,1]
	v_exp_f32_e32 v16, v28
	v_exp_f32_e32 v17, v29
	v_pk_mul_f32 v[20:21], v[28:29], v[20:21]
	v_pk_fma_f32 v[22:23], v[22:23], v[36:37], v[148:149] op_sel_hi:[1,0,1] neg_lo:[0,0,1] neg_hi:[0,0,1]
	v_add_f32_e32 v16, 1.0, v16
	v_add_f32_e32 v17, 1.0, v17
	v_rcp_f32_e32 v16, v16
	v_rcp_f32_e32 v17, v17
	v_pk_mul_f32 v[22:23], v[30:31], v[22:23]
	v_pk_fma_f32 v[18:19], v[18:19], v[36:37], v[152:153] op_sel_hi:[1,0,1] neg_lo:[0,0,1] neg_hi:[0,0,1]
	v_add_u32_e32 v32, 0xa0, v172
	v_pk_mul_f32 v[16:17], v[20:21], v[16:17]
	v_mad_i64_i32 v[32:33], s[52:53], v32, s31, v[156:157]
	v_cvt_pk_bf16_f32 v16, v16, v17
	v_exp_f32_e32 v17, v30
	v_lshl_add_u64 v[32:33], v[32:33], 0, v[158:159]
	v_add_f32_e32 v17, 1.0, v17
	v_rcp_f32_e32 v20, v17
	v_exp_f32_e32 v17, v31
	s_nop 0
	v_add_f32_e32 v17, 1.0, v17
	v_rcp_f32_e32 v21, v17
	s_nop 0
	v_pk_mul_f32 v[20:21], v[22:23], v[20:21]
	s_nop 0
	v_cvt_pk_bf16_f32 v17, v20, v21
	v_exp_f32_e32 v20, v24
	v_exp_f32_e32 v21, v25
	v_pk_mul_f32 v[22:23], v[26:27], v[18:19]
	v_pk_mul_f32 v[18:19], v[24:25], v[34:35]
	v_add_f32_e32 v20, 1.0, v20
	v_add_f32_e32 v21, 1.0, v21
	v_rcp_f32_e32 v20, v20
	v_rcp_f32_e32 v21, v21
	s_nop 0
	v_pk_mul_f32 v[18:19], v[18:19], v[20:21]
	s_nop 0
	v_cvt_pk_bf16_f32 v18, v18, v19
	v_exp_f32_e32 v19, v26
	s_nop 0
	v_add_f32_e32 v19, 1.0, v19
	v_rcp_f32_e32 v20, v19
	v_exp_f32_e32 v19, v27
	s_nop 0
	v_add_f32_e32 v19, 1.0, v19
	v_rcp_f32_e32 v21, v19
	s_nop 0
	v_pk_mul_f32 v[20:21], v[22:23], v[20:21]
	s_nop 0
	v_cvt_pk_bf16_f32 v19, v20, v21
	global_store_dwordx4 v[32:33], v[16:19], off
	ds_read_b32 v19, v168 offset:704
	s_waitcnt lgkmcnt(0)
	v_mul_f32_e32 v20, 0xbf317218, v19
	v_mul_f32_e32 v18, 0xbfb8aa3b, v19
	v_pk_fma_f32 v[12:13], v[12:13], v[18:19], v[146:147] op_sel_hi:[1,0,1] neg_lo:[0,0,1] neg_hi:[0,0,1]
	v_pk_fma_f32 v[14:15], v[14:15], v[18:19], v[144:145] op_sel_hi:[1,0,1] neg_lo:[0,0,1] neg_hi:[0,0,1]
	v_pk_fma_f32 v[10:11], v[10:11], v[18:19], v[112:113] op_sel_hi:[1,0,1] neg_lo:[0,0,1] neg_hi:[0,0,1]
	v_pk_fma_f32 v[8:9], v[8:9], v[18:19], v[114:115] op_sel_hi:[1,0,1] neg_lo:[0,0,1] neg_hi:[0,0,1]
	v_pk_fma_f32 v[18:19], v[0:1], v[20:21], v[154:155] op_sel_hi:[1,0,1] neg_lo:[0,0,1] neg_hi:[0,0,1]
	v_exp_f32_e32 v0, v12
	v_exp_f32_e32 v1, v13
	v_pk_fma_f32 v[4:5], v[4:5], v[20:21], v[150:151] op_sel_hi:[1,0,1] neg_lo:[0,0,1] neg_hi:[0,0,1]
	v_pk_fma_f32 v[6:7], v[6:7], v[20:21], v[148:149] op_sel_hi:[1,0,1] neg_lo:[0,0,1] neg_hi:[0,0,1]
	v_add_f32_e32 v0, 1.0, v0
	v_add_f32_e32 v1, 1.0, v1
	v_rcp_f32_e32 v0, v0
	v_rcp_f32_e32 v1, v1
	v_pk_mul_f32 v[4:5], v[12:13], v[4:5]
	v_pk_mul_f32 v[6:7], v[14:15], v[6:7]
	v_pk_fma_f32 v[2:3], v[2:3], v[20:21], v[152:153] op_sel_hi:[1,0,1] neg_lo:[0,0,1] neg_hi:[0,0,1]
	v_pk_mul_f32 v[0:1], v[4:5], v[0:1]
	v_add_u32_e32 v16, 0xb0, v172
	v_cvt_pk_bf16_f32 v0, v0, v1
	v_exp_f32_e32 v1, v14
	v_mad_i64_i32 v[16:17], s[52:53], v16, s31, v[156:157]
	v_lshl_add_u64 v[16:17], v[16:17], 0, v[158:159]
	v_add_f32_e32 v1, 1.0, v1
	v_rcp_f32_e32 v4, v1
	v_exp_f32_e32 v1, v15
	s_nop 0
	v_add_f32_e32 v1, 1.0, v1
	v_rcp_f32_e32 v5, v1
	s_nop 0
	v_pk_mul_f32 v[4:5], v[6:7], v[4:5]
	s_nop 0
	v_cvt_pk_bf16_f32 v1, v4, v5
	v_exp_f32_e32 v4, v8
	v_exp_f32_e32 v5, v9
	v_pk_mul_f32 v[6:7], v[10:11], v[2:3]
	v_pk_mul_f32 v[2:3], v[8:9], v[18:19]
	v_add_f32_e32 v4, 1.0, v4
	v_add_f32_e32 v5, 1.0, v5
	v_rcp_f32_e32 v4, v4
	v_rcp_f32_e32 v5, v5
	s_nop 0
	v_pk_mul_f32 v[2:3], v[2:3], v[4:5]
	s_nop 0
	v_cvt_pk_bf16_f32 v2, v2, v3
	v_exp_f32_e32 v3, v10
	s_nop 0
	v_add_f32_e32 v3, 1.0, v3
	v_rcp_f32_e32 v4, v3
	v_exp_f32_e32 v3, v11
	s_nop 0
	v_add_f32_e32 v3, 1.0, v3
	v_rcp_f32_e32 v5, v3
	s_nop 0
	v_pk_mul_f32 v[4:5], v[6:7], v[4:5]
	s_nop 0
	v_cvt_pk_bf16_f32 v3, v4, v5
	global_store_dwordx4 v[16:17], v[0:3], off
	s_cbranch_vccnz .LBB0_162
	s_andn2_b64 vcc, exec, s[0:1]
	s_cbranch_vccnz .LBB0_161
	s_barrier
	s_branch .LBB0_161

;     __device__ __forceinline__ Pre prefetch(const Unit& u, int tid) const { return prenorm_load(stats, u.pn * BM, sW + (size_t)(u.pn >> 4) * SW_ROWS + u.pm * BM, tid); }
;     __device__ __forceinline__ Pre prefetch(const Unit& u, int tid) const { return prenorm_load(stats, u.pm * BM, sW + (size_t)(u.pm >> 4) * SW_ROWS + u.pn * BM, tid); }
;     __device__ __forceinline__ Pre prefetch(const Unit& u, int tid) const { return prenorm_load(stats, u.pm * BM, sW + (size_t)(u.pm >> 4) * SW_ROWS + u.pn * BM, tid); }
; #define PG8_STAGE(bufoff, gbase, voff) do { _Pragma("unroll") for (int _i = 0; _i < 2; ++_i) \
;         __builtin_amdgcn_global_load_lds((const unsigned*)((const char*)(gbase) + (voff)[_i]), (LAS unsigned*)(lds + (bufoff) + ldsw + _i * 8192), 16, 0, 0); } while (0)
; #define PG8_LDA(dst, b, h) do { _Pragma("unroll") for (int m = 0; m < 4; ++m) _Pragma("unroll") for (int k = 0; k < 2; ++k) dst[m][k] = *(const LAS bf16x8*)(lds + PG8_SA(b, h) + aoff + m * 2048 + k * 1024); } while (0)
; #define PG8_WAIT_V(n) asm volatile("s_waitcnt vmcnt(" #n ")" ::: "memory")
; template <class Epi, class Sched>
; __device__ __forceinline__ void gemm_phase(LAS unsigned char* lds, const Gemm g, const Sched& S, const Epi& E, const int tid) {
;     ...
;         const bool has_next = S.next(ui + 1, nxt);
;         const char* nA = has_next ? (const char*)g.A + (size_t)nxt.pm * tstep : cA; const char* nB = has_next ? (const char*)g.Bt + (size_t)nxt.pn * tstep : cB;
;         const typename Epi::Pre pre = E.prefetch(cur, tid);
;         for (int t = 0; t < nt; t += 2) {
;             const bool last = (t == nt - 2);
;             const char* a1 = cA + (size_t)(t + 1) * kstep;
;             const char* a2 = last ? nA : cA + (size_t)(t + 2) * kstep; const char* b2 = last ? nB : cB + (size_t)(t + 2) * kstep;
;             const char* a3 = a2 + kstep; const char* b3 = b2 + kstep;
;             PG8_LDB(B0, 0, 0); PG8_LDB(B1, 0, 1); PG8_SCHED; PG8_LDA(At, 0, 0); PG8_STAGE(PG8_SA(1, 1), a1 + hstep, voffA);
;             PG8_WAIT_V(8); PG8_WAIT_L(0); PG8_BAR; PG8_MMA(0, 0, At, B0); PG8_MMA(0, 1, At, B1); PG8_BAR; PG8_SCHED;
;             PG8_LDA(At, 0, 1); PG8_STAGE(PG8_SB(0, 0), b2, voffB); PG8_STAGE(PG8_SB(0, 1), b2 + hstep, voffB); PG8_STAGE(PG8_SA(0, 0), a2, voffA);
;             PG8_WAIT_V(8); PG8_WAIT_L(0); PG8_BAR; PG8_MMA(1, 0, At, B0); PG8_MMA(1, 1, At, B1); PG8_BAR; PG8_SCHED;
.LBB0_265:
	s_or_b64 exec, exec, s[38:39]
	s_ashr_i32 s23, s22, 31
	s_lshl_b64 s[38:39], s[22:23], 19
	s_add_u32 s38, s46, s38
	s_addc_u32 s39, s47, s39
	s_and_b64 s[56:57], s[4:5], exec
	s_cselect_b32 s23, s39, s7
	s_cselect_b32 s56, s38, s6
	s_ashr_i32 s55, s54, 31
	s_lshl_b64 s[58:59], s[54:55], 19
	s_add_u32 s62, s35, s58
	s_addc_u32 s63, s84, s59
	s_and_b64 s[58:59], s[4:5], exec
	s_cselect_b32 s55, s63, s65
	s_cselect_b32 s57, s62, s64
	s_add_u32 s6, s6, 0x40080
	s_addc_u32 s7, s7, 0
	s_add_u32 s58, s64, 0x100
	s_addc_u32 s59, s65, 0
	s_mov_b32 s60, -2
	s_waitcnt vmcnt(0)
	s_add_u32 s61, s6, 0xfffc0080
	s_addc_u32 s64, s7, -1
	s_add_i32 s70, 0, 0x10000
	s_cmp_eq_u32 s60, 12
	s_cselect_b32 s67, s23, s64
	s_cselect_b32 s66, s56, s61
	v_add_u32_e32 v81, s70, v216
	s_cselect_b32 s65, s55, s59
	s_cselect_b32 s64, s57, s58
	s_add_i32 s61, 0, 0x14000
	ds_read_b128 v[88:91], v81
	ds_read_b128 v[92:95], v81 offset:1024
	ds_read_b128 v[144:147], v81 offset:2048
	ds_read_b128 v[148:151], v81 offset:3072
	v_add_u32_e32 v81, s61, v216
	ds_read_b128 v[152:155], v81
	ds_read_b128 v[156:159], v81 offset:1024
	ds_read_b128 v[178:181], v81 offset:2048
	ds_read_b128 v[182:185], v81 offset:3072
	v_lshl_add_u64 v[82:83], s[6:7], 0, v[174:175]
	s_add_i32 m0, s73, 0xc000
	ds_read_b128 v[186:189], v230
	ds_read_b128 v[198:201], v230 offset:1024
	ds_read_b128 v[202:205], v230 offset:2048
	ds_read_b128 v[206:209], v230 offset:3072
	ds_read_b128 v[234:237], v230 offset:4096
	ds_read_b128 v[238:241], v230 offset:5120
	ds_read_b128 v[242:245], v230 offset:6144
	ds_read_b128 v[246:249], v230 offset:7168
	global_load_lds_dwordx4 v[82:83], off
	v_lshl_add_u64 v[82:83], s[6:7], 0, v[176:177]
	s_add_i32 m0, s73, 0xe000
	s_nop 0
	global_load_lds_dwordx4 v[82:83], off
	s_waitcnt vmcnt(8)
	s_waitcnt lgkmcnt(0)
	s_barrier
	s_setprio 1
	s_waitcnt lgkmcnt(0)
	v_mfma_f32_16x16x32_bf16 v[140:143], v[88:91], v[186:189], 0
	v_mfma_f32_16x16x32_bf16 v[136:139], v[144:147], v[186:189], 0
	v_mfma_f32_16x16x32_bf16 v[124:127], v[88:91], v[202:205], 0
	v_mfma_f32_16x16x32_bf16 v[120:123], v[144:147], v[202:205], 0
	v_mfma_f32_16x16x32_bf16 v[108:111], v[88:91], v[234:237], 0
	v_mfma_f32_16x16x32_bf16 v[104:107], v[144:147], v[234:237], 0
	v_mfma_f32_16x16x32_bf16 v[82:85], v[88:91], v[242:245], 0
	v_mfma_f32_16x16x32_bf16 v[76:79], v[144:147], v[242:245], 0
	v_mfma_f32_16x16x32_bf16 v[140:143], v[92:95], v[198:201], v[140:143]
	v_mfma_f32_16x16x32_bf16 v[136:139], v[148:151], v[198:201], v[136:139]
	v_mfma_f32_16x16x32_bf16 v[124:127], v[92:95], v[206:209], v[124:127]
	v_mfma_f32_16x16x32_bf16 v[120:123], v[148:151], v[206:209], v[120:123]
	v_mfma_f32_16x16x32_bf16 v[108:111], v[92:95], v[238:241], v[108:111]
	v_mfma_f32_16x16x32_bf16 v[104:107], v[148:151], v[238:241], v[104:107]
	v_mfma_f32_16x16x32_bf16 v[82:85], v[92:95], v[246:249], v[82:85]
	v_mfma_f32_16x16x32_bf16 v[76:79], v[148:151], v[246:249], v[76:79]
	s_setprio 0
	s_setprio 1
	v_mfma_f32_16x16x32_bf16 v[132:135], v[152:155], v[186:189], 0
	v_mfma_f32_16x16x32_bf16 v[128:131], v[178:181], v[186:189], 0
	v_mfma_f32_16x16x32_bf16 v[116:119], v[152:155], v[202:205], 0
	v_mfma_f32_16x16x32_bf16 v[112:115], v[178:181], v[202:205], 0
	v_mfma_f32_16x16x32_bf16 v[100:103], v[152:155], v[234:237], 0
	v_mfma_f32_16x16x32_bf16 v[96:99], v[178:181], v[234:237], 0
	v_mfma_f32_16x16x32_bf16 v[68:71], v[152:155], v[242:245], 0
	v_mfma_f32_16x16x32_bf16 v[64:67], v[178:181], v[242:245], 0
	v_mfma_f32_16x16x32_bf16 v[132:135], v[156:159], v[198:201], v[132:135]
	v_mfma_f32_16x16x32_bf16 v[128:131], v[182:185], v[198:201], v[128:131]
	v_mfma_f32_16x16x32_bf16 v[116:119], v[156:159], v[206:209], v[116:119]
	v_mfma_f32_16x16x32_bf16 v[112:115], v[182:185], v[206:209], v[112:115]
	v_mfma_f32_16x16x32_bf16 v[100:103], v[156:159], v[238:241], v[100:103]
	v_mfma_f32_16x16x32_bf16 v[96:99], v[182:185], v[238:241], v[96:99]
	v_mfma_f32_16x16x32_bf16 v[68:71], v[156:159], v[246:249], v[68:71]
	v_mfma_f32_16x16x32_bf16 v[64:67], v[182:185], v[246:249], v[64:67]
	s_setprio 0
	s_barrier
	s_add_i32 s70, s70, s12
	v_lshl_add_u64 v[190:191], s[64:65], 0, v[164:165]
	s_mov_b32 m0, s70
	ds_read_b128 v[186:189], v230 offset:16384
	ds_read_b128 v[198:201], v230 offset:17408
	ds_read_b128 v[202:205], v230 offset:18432
	ds_read_b128 v[206:209], v230 offset:19456
	ds_read_b128 v[234:237], v230 offset:20480
	ds_read_b128 v[238:241], v230 offset:21504
	ds_read_b128 v[242:245], v230 offset:22528
	ds_read_b128 v[246:249], v230 offset:23552
	global_load_lds_dwordx4 v[190:191], off
	s_add_i32 m0, s70, 0x2000
	s_add_u32 s70, s64, 0x40000
	v_lshl_add_u64 v[250:251], s[64:65], 0, v[168:169]
	s_addc_u32 s71, s65, 0
	s_add_i32 s61, s61, s12
	global_load_lds_dwordx4 v[250:251], off
	v_lshl_add_u64 v[86:87], s[70:71], 0, v[164:165]
	s_mov_b32 m0, s61
	v_lshl_add_u64 v[224:225], s[66:67], 0, v[162:163]
	global_load_lds_dwordx4 v[86:87], off
	v_lshl_add_u64 v[86:87], s[70:71], 0, v[168:169]
	s_add_i32 m0, s61, 0x2000
	v_lshl_add_u64 v[226:227], s[66:67], 0, v[166:167]
	global_load_lds_dwordx4 v[86:87], off
	s_mov_b32 m0, s73
	s_nop 0
	global_load_lds_dwordx4 v[224:225], off
	s_mov_b32 m0, s74
	s_nop 0
	global_load_lds_dwordx4 v[226:227], off
	s_waitcnt vmcnt(8)
	s_waitcnt lgkmcnt(0)
	s_barrier
; #define PG8_STAGE(bufoff, gbase, voff) do { _Pragma("unroll") for (int _i = 0; _i < 2; ++_i) \
;         __builtin_amdgcn_global_load_lds((const unsigned*)((const char*)(gbase) + (voff)[_i]), (LAS unsigned*)(lds + (bufoff) + ldsw + _i * 8192), 16, 0, 0); } while (0)
; #define PG8_LDA(dst, b, h) do { _Pragma("unroll") for (int m = 0; m < 4; ++m) _Pragma("unroll") for (int k = 0; k < 2; ++k) dst[m][k] = *(const LAS bf16x8*)(lds + PG8_SA(b, h) + aoff + m * 2048 + k * 1024); } while (0)
; #define PG8_LDB(dst, b, h) do { _Pragma("unroll") for (int n = 0; n < 2; ++n) _Pragma("unroll") for (int k = 0; k < 2; ++k) dst[n][k] = *(const LAS bf16x8*)(lds + PG8_SB(b, h) + boff + n * 2048 + k * 1024); } while (0)
; #define PG8_MMA(ai, bj, At, Bt) do { __builtin_amdgcn_s_setprio(1); _Pragma("unroll") for (int m = 0; m < 4; ++m) _Pragma("unroll") for (int n = 0; n < 2; ++n) _Pragma("unroll") for (int k = 0; k < 2; ++k) \
;         acc[ai][bj][m][n] = __builtin_amdgcn_mfma_f32_16x16x32_bf16(Bt[n][k], At[m][k], acc[ai][bj][m][n], 0, 0, 0); __builtin_amdgcn_s_setprio(0); } while (0)
; #define PG8_WAIT_V(n) asm volatile("s_waitcnt vmcnt(" #n ")" ::: "memory")
; #define PG8_WAIT_L(n) asm volatile("s_waitcnt lgkmcnt(" #n ")" ::: "memory")
; #define PG8_BAR __builtin_amdgcn_s_barrier()
; #define PG8_SCHED __builtin_amdgcn_sched_barrier(0)
; template <class Epi, class Sched>
; __device__ __forceinline__ void gemm_phase(LAS unsigned char* lds, const Gemm g, const Sched& S, const Epi& E, const int tid) {
;     ...
;             PG8_WAIT_V(8); PG8_WAIT_L(0); PG8_BAR; PG8_MMA(1, 0, At, B0); PG8_MMA(1, 1, At, B1); PG8_BAR; PG8_SCHED;
;             PG8_LDB(B0, 1, 0); PG8_LDB(B1, 1, 1); PG8_SCHED; PG8_LDA(At, 1, 0); PG8_STAGE(PG8_SA(0, 1), a2 + hstep, voffA);
;             PG8_WAIT_V(8); PG8_WAIT_L(0); PG8_BAR; PG8_MMA(0, 0, At, B0); PG8_MMA(0, 1, At, B1); PG8_BAR; PG8_SCHED;
	s_setprio 1
	s_waitcnt lgkmcnt(0)
	v_mfma_f32_16x16x32_bf16 v[60:63], v[88:91], v[186:189], 0
	v_mfma_f32_16x16x32_bf16 v[56:59], v[144:147], v[186:189], 0
	v_mfma_f32_16x16x32_bf16 v[44:47], v[88:91], v[202:205], 0
	v_mfma_f32_16x16x32_bf16 v[40:43], v[144:147], v[202:205], 0
	v_mfma_f32_16x16x32_bf16 v[28:31], v[88:91], v[234:237], 0
	v_mfma_f32_16x16x32_bf16 v[24:27], v[144:147], v[234:237], 0
	v_mfma_f32_16x16x32_bf16 v[12:15], v[88:91], v[242:245], 0
	v_mfma_f32_16x16x32_bf16 v[8:11], v[144:147], v[242:245], 0
	v_mfma_f32_16x16x32_bf16 v[60:63], v[92:95], v[198:201], v[60:63]
	v_mfma_f32_16x16x32_bf16 v[56:59], v[148:151], v[198:201], v[56:59]
	v_mfma_f32_16x16x32_bf16 v[44:47], v[92:95], v[206:209], v[44:47]
	v_mfma_f32_16x16x32_bf16 v[40:43], v[148:151], v[206:209], v[40:43]
	v_mfma_f32_16x16x32_bf16 v[28:31], v[92:95], v[238:241], v[28:31]
	v_mfma_f32_16x16x32_bf16 v[24:27], v[148:151], v[238:241], v[24:27]
	v_mfma_f32_16x16x32_bf16 v[12:15], v[92:95], v[246:249], v[12:15]
	v_mfma_f32_16x16x32_bf16 v[8:11], v[148:151], v[246:249], v[8:11]
	s_setprio 0
	s_setprio 1
	v_mfma_f32_16x16x32_bf16 v[52:55], v[152:155], v[186:189], 0
	v_mfma_f32_16x16x32_bf16 v[48:51], v[178:181], v[186:189], 0
	v_mfma_f32_16x16x32_bf16 v[36:39], v[152:155], v[202:205], 0
	v_mfma_f32_16x16x32_bf16 v[32:35], v[178:181], v[202:205], 0
	v_mfma_f32_16x16x32_bf16 v[20:23], v[152:155], v[234:237], 0
	v_mfma_f32_16x16x32_bf16 v[16:19], v[178:181], v[234:237], 0
	v_mfma_f32_16x16x32_bf16 v[4:7], v[152:155], v[242:245], 0
	v_mfma_f32_16x16x32_bf16 v[0:3], v[178:181], v[242:245], 0
	v_mfma_f32_16x16x32_bf16 v[52:55], v[156:159], v[198:201], v[52:55]
	v_mfma_f32_16x16x32_bf16 v[48:51], v[182:185], v[198:201], v[48:51]
	v_mfma_f32_16x16x32_bf16 v[36:39], v[156:159], v[206:209], v[36:39]
	v_mfma_f32_16x16x32_bf16 v[32:35], v[182:185], v[206:209], v[32:35]
	v_mfma_f32_16x16x32_bf16 v[20:23], v[156:159], v[238:241], v[20:23]
	v_mfma_f32_16x16x32_bf16 v[16:19], v[182:185], v[238:241], v[16:19]
	v_mfma_f32_16x16x32_bf16 v[4:7], v[156:159], v[246:249], v[4:7]
	v_mfma_f32_16x16x32_bf16 v[0:3], v[182:185], v[246:249], v[0:3]
	s_setprio 0
	s_barrier
	s_add_i32 s61, 0, 0x18000
	v_add_u32_e32 v81, s61, v216
	s_add_i32 s70, 0, 0x1c000
	ds_read_b128 v[88:91], v81
	ds_read_b128 v[92:95], v81 offset:1024
	ds_read_b128 v[144:147], v81 offset:2048
	ds_read_b128 v[148:151], v81 offset:3072
	v_add_u32_e32 v81, s70, v216
	ds_read_b128 v[152:155], v81
	ds_read_b128 v[156:159], v81 offset:1024
	ds_read_b128 v[178:181], v81 offset:2048
	ds_read_b128 v[182:185], v81 offset:3072
	s_add_u32 s66, s66, 0x40000
	s_addc_u32 s67, s67, 0
	s_mov_b32 m0, s75
	v_lshl_add_u64 v[86:87], s[66:67], 0, v[162:163]
	ds_read_b128 v[186:189], v230 offset:32768
	ds_read_b128 v[198:201], v230 offset:33792
	ds_read_b128 v[202:205], v230 offset:34816
	ds_read_b128 v[206:209], v230 offset:35840
	ds_read_b128 v[234:237], v230 offset:36864
	ds_read_b128 v[238:241], v230 offset:37888
	ds_read_b128 v[242:245], v230 offset:38912
	ds_read_b128 v[246:249], v230 offset:39936
	global_load_lds_dwordx4 v[86:87], off
	v_lshl_add_u64 v[86:87], s[66:67], 0, v[166:167]
	s_mov_b32 m0, s81
	s_nop 0
	global_load_lds_dwordx4 v[86:87], off
	s_waitcnt vmcnt(8)
	s_waitcnt lgkmcnt(0)
	s_barrier
	s_setprio 1
	s_waitcnt lgkmcnt(0)
	v_mfma_f32_16x16x32_bf16 v[140:143], v[88:91], v[186:189], v[140:143]
	v_mfma_f32_16x16x32_bf16 v[136:139], v[144:147], v[186:189], v[136:139]
	v_mfma_f32_16x16x32_bf16 v[124:127], v[88:91], v[202:205], v[124:127]
	v_mfma_f32_16x16x32_bf16 v[120:123], v[144:147], v[202:205], v[120:123]
	v_mfma_f32_16x16x32_bf16 v[108:111], v[88:91], v[234:237], v[108:111]
	v_mfma_f32_16x16x32_bf16 v[104:107], v[144:147], v[234:237], v[104:107]
	v_mfma_f32_16x16x32_bf16 v[82:85], v[88:91], v[242:245], v[82:85]
	v_mfma_f32_16x16x32_bf16 v[76:79], v[144:147], v[242:245], v[76:79]
	v_mfma_f32_16x16x32_bf16 v[140:143], v[92:95], v[198:201], v[140:143]
	v_mfma_f32_16x16x32_bf16 v[136:139], v[148:151], v[198:201], v[136:139]
	v_mfma_f32_16x16x32_bf16 v[124:127], v[92:95], v[206:209], v[124:127]
	v_mfma_f32_16x16x32_bf16 v[120:123], v[148:151], v[206:209], v[120:123]
	v_mfma_f32_16x16x32_bf16 v[108:111], v[92:95], v[238:241], v[108:111]
	v_mfma_f32_16x16x32_bf16 v[104:107], v[148:151], v[238:241], v[104:107]
	v_mfma_f32_16x16x32_bf16 v[84:87], v[92:95], v[246:249], v[82:85]
	v_mfma_f32_16x16x32_bf16 v[76:79], v[148:151], v[246:249], v[76:79]
	s_setprio 0
	s_setprio 1
	v_mfma_f32_16x16x32_bf16 v[132:135], v[152:155], v[186:189], v[132:135]
	v_mfma_f32_16x16x32_bf16 v[128:131], v[178:181], v[186:189], v[128:131]
	v_mfma_f32_16x16x32_bf16 v[116:119], v[152:155], v[202:205], v[116:119]
	v_mfma_f32_16x16x32_bf16 v[112:115], v[178:181], v[202:205], v[112:115]
	v_mfma_f32_16x16x32_bf16 v[100:103], v[152:155], v[234:237], v[100:103]
	v_mfma_f32_16x16x32_bf16 v[96:99], v[178:181], v[234:237], v[96:99]
	v_mfma_f32_16x16x32_bf16 v[68:71], v[152:155], v[242:245], v[68:71]
	v_mfma_f32_16x16x32_bf16 v[64:67], v[178:181], v[242:245], v[64:67]
	v_mfma_f32_16x16x32_bf16 v[132:135], v[156:159], v[198:201], v[132:135]
	v_mfma_f32_16x16x32_bf16 v[128:131], v[182:185], v[198:201], v[128:131]
	v_mfma_f32_16x16x32_bf16 v[116:119], v[156:159], v[206:209], v[116:119]
	v_mfma_f32_16x16x32_bf16 v[112:115], v[182:185], v[206:209], v[112:115]
	v_mfma_f32_16x16x32_bf16 v[100:103], v[156:159], v[238:241], v[100:103]
	v_mfma_f32_16x16x32_bf16 v[96:99], v[182:185], v[238:241], v[96:99]
	v_mfma_f32_16x16x32_bf16 v[68:71], v[156:159], v[246:249], v[68:71]
	v_mfma_f32_16x16x32_bf16 v[64:67], v[182:185], v[246:249], v[64:67]
	s_setprio 0
	s_barrier
; #define PG8_STAGE(bufoff, gbase, voff) do { _Pragma("unroll") for (int _i = 0; _i < 2; ++_i) \
;         __builtin_amdgcn_global_load_lds((const unsigned*)((const char*)(gbase) + (voff)[_i]), (LAS unsigned*)(lds + (bufoff) + ldsw + _i * 8192), 16, 0, 0); } while (0)
; #define PG8_LDA(dst, b, h) do { _Pragma("unroll") for (int m = 0; m < 4; ++m) _Pragma("unroll") for (int k = 0; k < 2; ++k) dst[m][k] = *(const LAS bf16x8*)(lds + PG8_SA(b, h) + aoff + m * 2048 + k * 1024); } while (0)
; #define PG8_MMA(ai, bj, At, Bt) do { __builtin_amdgcn_s_setprio(1); _Pragma("unroll") for (int m = 0; m < 4; ++m) _Pragma("unroll") for (int n = 0; n < 2; ++n) _Pragma("unroll") for (int k = 0; k < 2; ++k) \
;         acc[ai][bj][m][n] = __builtin_amdgcn_mfma_f32_16x16x32_bf16(Bt[n][k], At[m][k], acc[ai][bj][m][n], 0, 0, 0); __builtin_amdgcn_s_setprio(0); } while (0)
; #define PG8_WAIT_V(n) asm volatile("s_waitcnt vmcnt(" #n ")" ::: "memory")
; #define PG8_WAIT_L(n) asm volatile("s_waitcnt lgkmcnt(" #n ")" ::: "memory")
; #define PG8_BAR __builtin_amdgcn_s_barrier()
; #define PG8_SCHED __builtin_amdgcn_sched_barrier(0)
; template <class Epi, class Sched>
; __device__ __forceinline__ void gemm_phase(LAS unsigned char* lds, const Gemm g, const Sched& S, const Epi& E, const int tid) {
;     ...
;             PG8_LDA(At, 1, 1); PG8_STAGE(PG8_SB(1, 0), b3, voffB); PG8_STAGE(PG8_SB(1, 1), b3 + hstep, voffB); PG8_STAGE(PG8_SA(1, 0), a3, voffA);
;             PG8_WAIT_V(8); PG8_WAIT_L(0); PG8_BAR; PG8_MMA(1, 0, At, B0); PG8_MMA(1, 1, At, B1); PG8_BAR; PG8_SCHED;
;         }
	s_add_i32 s61, s61, s12
	v_lshl_add_u64 v[82:83], v[190:191], 0, s[68:69]
	s_mov_b32 m0, s61
	ds_read_b128 v[186:189], v230 offset:49152
	ds_read_b128 v[198:201], v230 offset:50176
	ds_read_b128 v[202:205], v230 offset:51200
	ds_read_b128 v[206:209], v230 offset:52224
	ds_read_b128 v[234:237], v230 offset:53248
	ds_read_b128 v[238:241], v230 offset:54272
	ds_read_b128 v[242:245], v230 offset:55296
	ds_read_b128 v[246:249], v230 offset:56320
	global_load_lds_dwordx4 v[82:83], off
	s_add_i32 m0, s61, 0x2000
	s_add_u32 s64, s64, 0x40080
	v_lshl_add_u64 v[82:83], v[250:251], 0, s[68:69]
	s_addc_u32 s65, s65, 0
	s_add_i32 s61, s70, s12
	global_load_lds_dwordx4 v[82:83], off
	v_lshl_add_u64 v[82:83], s[64:65], 0, v[164:165]
	s_mov_b32 m0, s61
	s_nop 0
	global_load_lds_dwordx4 v[82:83], off
	v_lshl_add_u64 v[82:83], s[64:65], 0, v[168:169]
	s_add_i32 m0, s61, 0x2000
	s_nop 0
	global_load_lds_dwordx4 v[82:83], off
	v_lshl_add_u64 v[82:83], v[224:225], 0, s[68:69]
	s_mov_b32 m0, s82
	s_nop 0
	global_load_lds_dwordx4 v[82:83], off
	v_lshl_add_u64 v[82:83], v[226:227], 0, s[68:69]
	s_mov_b32 m0, s83
	s_nop 0
	global_load_lds_dwordx4 v[82:83], off
	s_waitcnt vmcnt(8)
	s_waitcnt lgkmcnt(0)
	s_barrier
	s_setprio 1
	s_waitcnt lgkmcnt(0)
	v_mfma_f32_16x16x32_bf16 v[60:63], v[88:91], v[186:189], v[60:63]
	v_mfma_f32_16x16x32_bf16 v[56:59], v[144:147], v[186:189], v[56:59]
	v_mfma_f32_16x16x32_bf16 v[44:47], v[88:91], v[202:205], v[44:47]
	v_mfma_f32_16x16x32_bf16 v[40:43], v[144:147], v[202:205], v[40:43]
	v_mfma_f32_16x16x32_bf16 v[28:31], v[88:91], v[234:237], v[28:31]
	v_mfma_f32_16x16x32_bf16 v[24:27], v[144:147], v[234:237], v[24:27]
	v_mfma_f32_16x16x32_bf16 v[12:15], v[88:91], v[242:245], v[12:15]
	v_mfma_f32_16x16x32_bf16 v[8:11], v[144:147], v[242:245], v[8:11]
	v_mfma_f32_16x16x32_bf16 v[60:63], v[92:95], v[198:201], v[60:63]
	v_mfma_f32_16x16x32_bf16 v[56:59], v[148:151], v[198:201], v[56:59]
	v_mfma_f32_16x16x32_bf16 v[44:47], v[92:95], v[206:209], v[44:47]
	v_mfma_f32_16x16x32_bf16 v[40:43], v[148:151], v[206:209], v[40:43]
	v_mfma_f32_16x16x32_bf16 v[28:31], v[92:95], v[238:241], v[28:31]
	v_mfma_f32_16x16x32_bf16 v[24:27], v[148:151], v[238:241], v[24:27]
	v_mfma_f32_16x16x32_bf16 v[12:15], v[92:95], v[246:249], v[12:15]
	v_mfma_f32_16x16x32_bf16 v[8:11], v[148:151], v[246:249], v[8:11]
	s_setprio 0
	s_setprio 1
	v_mfma_f32_16x16x32_bf16 v[52:55], v[152:155], v[186:189], v[52:55]
	v_mfma_f32_16x16x32_bf16 v[48:51], v[178:181], v[186:189], v[48:51]
	v_mfma_f32_16x16x32_bf16 v[36:39], v[152:155], v[202:205], v[36:39]
	v_mfma_f32_16x16x32_bf16 v[32:35], v[178:181], v[202:205], v[32:35]
	v_mfma_f32_16x16x32_bf16 v[20:23], v[152:155], v[234:237], v[20:23]
	v_mfma_f32_16x16x32_bf16 v[16:19], v[178:181], v[234:237], v[16:19]
	v_mfma_f32_16x16x32_bf16 v[4:7], v[152:155], v[242:245], v[4:7]
	v_mfma_f32_16x16x32_bf16 v[0:3], v[178:181], v[242:245], v[0:3]
	v_mfma_f32_16x16x32_bf16 v[52:55], v[156:159], v[198:201], v[52:55]
	v_mfma_f32_16x16x32_bf16 v[48:51], v[182:185], v[198:201], v[48:51]
	v_mfma_f32_16x16x32_bf16 v[36:39], v[156:159], v[206:209], v[36:39]
	v_mfma_f32_16x16x32_bf16 v[32:35], v[182:185], v[206:209], v[32:35]
	v_mfma_f32_16x16x32_bf16 v[20:23], v[156:159], v[238:241], v[20:23]
	v_mfma_f32_16x16x32_bf16 v[16:19], v[182:185], v[238:241], v[16:19]
	v_mfma_f32_16x16x32_bf16 v[4:7], v[156:159], v[246:249], v[4:7]
	v_mfma_f32_16x16x32_bf16 v[0:3], v[182:185], v[246:249], v[0:3]
	s_setprio 0
	s_barrier
	s_add_i32 s60, s60, 2
	s_add_u32 s6, s6, 0x100
	s_addc_u32 s7, s7, 0
	s_add_u32 s58, s58, 0x100
	s_addc_u32 s59, s59, 0
	s_cmp_gt_u32 s60, 13

;     __device__ __forceinline__ Pre prefetch(const Unit& u, int tid) const { return prenorm_load(stats, u.pn * BM, sW + (size_t)(u.pn >> 4) * SW_ROWS + u.pm * BM, tid); }
;     __device__ __forceinline__ Pre prefetch(const Unit& u, int tid) const { return prenorm_load(stats, u.pm * BM, sW + (size_t)(u.pm >> 4) * SW_ROWS + u.pn * BM, tid); }
;     __device__ __forceinline__ Pre prefetch(const Unit& u, int tid) const { return prenorm_load(stats, u.pm * BM, sW + (size_t)(u.pm >> 4) * SW_ROWS + u.pn * BM, tid); }
; #define PG8_STAGE(bufoff, gbase, voff) do { _Pragma("unroll") for (int _i = 0; _i < 2; ++_i) \
;         __builtin_amdgcn_global_load_lds((const unsigned*)((const char*)(gbase) + (voff)[_i]), (LAS unsigned*)(lds + (bufoff) + ldsw + _i * 8192), 16, 0, 0); } while (0)
; #define PG8_LDA(dst, b, h) do { _Pragma("unroll") for (int m = 0; m < 4; ++m) _Pragma("unroll") for (int k = 0; k < 2; ++k) dst[m][k] = *(const LAS bf16x8*)(lds + PG8_SA(b, h) + aoff + m * 2048 + k * 1024); } while (0)
; #define PG8_WAIT_V(n) asm volatile("s_waitcnt vmcnt(" #n ")" ::: "memory")
; template <class Epi, class Sched>
; __device__ __forceinline__ void gemm_phase(LAS unsigned char* lds, const Gemm g, const Sched& S, const Epi& E, const int tid) {
;     ...
;         const bool has_next = S.next(ui + 1, nxt);
;         const char* nA = has_next ? (const char*)g.A + (size_t)nxt.pm * tstep : cA; const char* nB = has_next ? (const char*)g.Bt + (size_t)nxt.pn * tstep : cB;
;         const typename Epi::Pre pre = E.prefetch(cur, tid);
;         for (int t = 0; t < nt; t += 2) {
;             const bool last = (t == nt - 2);
;             const char* a1 = cA + (size_t)(t + 1) * kstep;
;             const char* a2 = last ? nA : cA + (size_t)(t + 2) * kstep; const char* b2 = last ? nB : cB + (size_t)(t + 2) * kstep;
;             const char* a3 = a2 + kstep; const char* b3 = b2 + kstep;
;             PG8_LDB(B0, 0, 0); PG8_LDB(B1, 0, 1); PG8_SCHED; PG8_LDA(At, 0, 0); PG8_STAGE(PG8_SA(1, 1), a1 + hstep, voffA);
;             PG8_WAIT_V(8); PG8_WAIT_L(0); PG8_BAR; PG8_MMA(0, 0, At, B0); PG8_MMA(0, 1, At, B1); PG8_BAR; PG8_SCHED;
;             PG8_LDA(At, 0, 1); PG8_STAGE(PG8_SB(0, 0), b2, voffB); PG8_STAGE(PG8_SB(0, 1), b2 + hstep, voffB); PG8_STAGE(PG8_SA(0, 0), a2, voffA);
;             PG8_WAIT_V(8); PG8_WAIT_L(0); PG8_BAR; PG8_MMA(1, 0, At, B0); PG8_MMA(1, 1, At, B1); PG8_BAR; PG8_SCHED;
.LBB0_325:
	s_or_b64 exec, exec, s[50:51]
	s_ashr_i32 s39, s38, 31
	s_lshl_b64 s[50:51], s[38:39], 19
	s_add_u32 s50, s85, s50
	s_addc_u32 s51, s86, s51
	s_and_b64 s[54:55], s[4:5], exec
	s_cselect_b32 s39, s51, s63
	s_cselect_b32 s74, s50, s62
	s_ashr_i32 s23, s22, 31
	s_lshl_b64 s[54:55], s[22:23], 19
	s_add_u32 s54, s46, s54
	s_addc_u32 s55, s47, s55
	s_and_b64 s[66:67], s[4:5], exec
	s_cselect_b32 s23, s55, s65
	s_cselect_b32 s75, s54, s64
	s_add_u32 s62, s62, 0x40080
	s_addc_u32 s63, s63, 0
	s_add_u32 s78, s64, 0x100
	s_addc_u32 s79, s65, 0
	s_mov_b32 s81, -2
	s_waitcnt vmcnt(0)
	s_waitcnt lgkmcnt(0)
	s_add_u32 s64, s62, 0xfffc0080
	s_addc_u32 s65, s63, -1
	s_add_i32 s82, 0, 0x10000
	s_cmp_eq_u32 s81, 12
	s_cselect_b32 s67, s39, s65
	s_cselect_b32 s66, s74, s64
	v_add_u32_e32 v69, s82, v154
	s_cselect_b32 s65, s23, s79
	s_cselect_b32 s64, s75, s78
	s_add_i32 s90, 0, 0x14000
	ds_read_b128 v[70:73], v69
	ds_read_b128 v[74:77], v69 offset:1024
	ds_read_b128 v[172:175], v69 offset:2048
	ds_read_b128 v[176:179], v69 offset:3072
	v_add_u32_e32 v69, s90, v154
	ds_read_b128 v[180:183], v69
	ds_read_b128 v[184:187], v69 offset:1024
	ds_read_b128 v[188:191], v69 offset:2048
	ds_read_b128 v[198:201], v69 offset:3072
	v_lshl_add_u64 v[78:79], s[62:63], 0, v[144:145]
	s_add_i32 m0, s53, 0xc000
	ds_read_b128 v[202:205], v171
	ds_read_b128 v[206:209], v171 offset:1024
	ds_read_b128 v[210:213], v171 offset:2048
	ds_read_b128 v[214:217], v171 offset:3072
	ds_read_b128 v[218:221], v171 offset:4096
	ds_read_b128 v[230:233], v171 offset:5120
	ds_read_b128 v[234:237], v171 offset:6144
	ds_read_b128 v[238:241], v171 offset:7168
	global_load_lds_dwordx4 v[78:79], off
	v_lshl_add_u64 v[78:79], s[62:63], 0, v[146:147]
	s_add_i32 m0, s53, 0xe000
	s_nop 0
	global_load_lds_dwordx4 v[78:79], off
	s_waitcnt vmcnt(8)
	s_waitcnt lgkmcnt(0)
	s_barrier
	s_setprio 1
	s_waitcnt lgkmcnt(0)
	v_mfma_f32_16x16x32_bf16 v[140:143], v[70:73], v[202:205], 0
	v_mfma_f32_16x16x32_bf16 v[136:139], v[172:175], v[202:205], 0
	v_mfma_f32_16x16x32_bf16 v[132:135], v[70:73], v[210:213], 0
	v_mfma_f32_16x16x32_bf16 v[128:131], v[172:175], v[210:213], 0
	v_mfma_f32_16x16x32_bf16 v[116:119], v[70:73], v[218:221], 0
	v_mfma_f32_16x16x32_bf16 v[112:115], v[172:175], v[218:221], 0
	v_mfma_f32_16x16x32_bf16 v[100:103], v[70:73], v[234:237], 0
	v_mfma_f32_16x16x32_bf16 v[96:99], v[172:175], v[234:237], 0
	v_mfma_f32_16x16x32_bf16 v[140:143], v[74:77], v[206:209], v[140:143]
	v_mfma_f32_16x16x32_bf16 v[136:139], v[176:179], v[206:209], v[136:139]
	v_mfma_f32_16x16x32_bf16 v[132:135], v[74:77], v[214:217], v[132:135]
	v_mfma_f32_16x16x32_bf16 v[128:131], v[176:179], v[214:217], v[128:131]
	v_mfma_f32_16x16x32_bf16 v[116:119], v[74:77], v[230:233], v[116:119]
	v_mfma_f32_16x16x32_bf16 v[112:115], v[176:179], v[230:233], v[112:115]
	v_mfma_f32_16x16x32_bf16 v[100:103], v[74:77], v[238:241], v[100:103]
	v_mfma_f32_16x16x32_bf16 v[96:99], v[176:179], v[238:241], v[96:99]
	s_setprio 0
	s_setprio 1
	v_mfma_f32_16x16x32_bf16 v[124:127], v[180:183], v[202:205], 0
	v_mfma_f32_16x16x32_bf16 v[120:123], v[188:191], v[202:205], 0
	v_mfma_f32_16x16x32_bf16 v[108:111], v[180:183], v[210:213], 0
	v_mfma_f32_16x16x32_bf16 v[104:107], v[188:191], v[210:213], 0
	v_mfma_f32_16x16x32_bf16 v[92:95], v[180:183], v[218:221], 0
	v_mfma_f32_16x16x32_bf16 v[88:91], v[188:191], v[218:221], 0
	v_mfma_f32_16x16x32_bf16 v[84:87], v[180:183], v[234:237], 0
	v_mfma_f32_16x16x32_bf16 v[78:81], v[188:191], v[234:237], 0
	v_mfma_f32_16x16x32_bf16 v[124:127], v[184:187], v[206:209], v[124:127]
	v_mfma_f32_16x16x32_bf16 v[120:123], v[198:201], v[206:209], v[120:123]
	v_mfma_f32_16x16x32_bf16 v[108:111], v[184:187], v[214:217], v[108:111]
	v_mfma_f32_16x16x32_bf16 v[104:107], v[198:201], v[214:217], v[104:107]
	v_mfma_f32_16x16x32_bf16 v[92:95], v[184:187], v[230:233], v[92:95]
	v_mfma_f32_16x16x32_bf16 v[88:91], v[198:201], v[230:233], v[88:91]
	v_mfma_f32_16x16x32_bf16 v[84:87], v[184:187], v[238:241], v[84:87]
	v_mfma_f32_16x16x32_bf16 v[78:81], v[198:201], v[238:241], v[78:81]
	s_setprio 0
	s_barrier
	s_add_i32 s82, s82, s52
	v_lshl_add_u64 v[224:225], s[64:65], 0, v[164:165]
	s_mov_b32 m0, s82
	ds_read_b128 v[202:205], v171 offset:16384
	ds_read_b128 v[206:209], v171 offset:17408
	ds_read_b128 v[210:213], v171 offset:18432
	ds_read_b128 v[214:217], v171 offset:19456
	ds_read_b128 v[218:221], v171 offset:20480
	ds_read_b128 v[230:233], v171 offset:21504
	ds_read_b128 v[234:237], v171 offset:22528
	ds_read_b128 v[238:241], v171 offset:23552
	global_load_lds_dwordx4 v[224:225], off
	s_add_i32 m0, s82, 0x2000
	s_add_u32 s82, s64, 0x40000
	v_lshl_add_u64 v[226:227], s[64:65], 0, v[168:169]
	s_addc_u32 s83, s65, 0
	s_add_i32 s90, s90, s52
	global_load_lds_dwordx4 v[226:227], off
	v_lshl_add_u64 v[82:83], s[82:83], 0, v[164:165]
	s_mov_b32 m0, s90
	v_lshl_add_u64 v[242:243], s[66:67], 0, v[162:163]
	global_load_lds_dwordx4 v[82:83], off
	v_lshl_add_u64 v[82:83], s[82:83], 0, v[168:169]
	s_add_i32 m0, s90, 0x2000
	v_lshl_add_u64 v[244:245], s[66:67], 0, v[166:167]
	global_load_lds_dwordx4 v[82:83], off
	s_mov_b32 m0, s53
	s_nop 0
	global_load_lds_dwordx4 v[242:243], off
	s_mov_b32 m0, s56
	s_nop 0
	global_load_lds_dwordx4 v[244:245], off
	s_waitcnt vmcnt(8)
	s_waitcnt lgkmcnt(0)
	s_barrier
; #define PG8_STAGE(bufoff, gbase, voff) do { _Pragma("unroll") for (int _i = 0; _i < 2; ++_i) \
;         __builtin_amdgcn_global_load_lds((const unsigned*)((const char*)(gbase) + (voff)[_i]), (LAS unsigned*)(lds + (bufoff) + ldsw + _i * 8192), 16, 0, 0); } while (0)
; #define PG8_LDA(dst, b, h) do { _Pragma("unroll") for (int m = 0; m < 4; ++m) _Pragma("unroll") for (int k = 0; k < 2; ++k) dst[m][k] = *(const LAS bf16x8*)(lds + PG8_SA(b, h) + aoff + m * 2048 + k * 1024); } while (0)
; #define PG8_LDB(dst, b, h) do { _Pragma("unroll") for (int n = 0; n < 2; ++n) _Pragma("unroll") for (int k = 0; k < 2; ++k) dst[n][k] = *(const LAS bf16x8*)(lds + PG8_SB(b, h) + boff + n * 2048 + k * 1024); } while (0)
; #define PG8_MMA(ai, bj, At, Bt) do { __builtin_amdgcn_s_setprio(1); _Pragma("unroll") for (int m = 0; m < 4; ++m) _Pragma("unroll") for (int n = 0; n < 2; ++n) _Pragma("unroll") for (int k = 0; k < 2; ++k) \
;         acc[ai][bj][m][n] = __builtin_amdgcn_mfma_f32_16x16x32_bf16(Bt[n][k], At[m][k], acc[ai][bj][m][n], 0, 0, 0); __builtin_amdgcn_s_setprio(0); } while (0)
; #define PG8_WAIT_V(n) asm volatile("s_waitcnt vmcnt(" #n ")" ::: "memory")
; #define PG8_WAIT_L(n) asm volatile("s_waitcnt lgkmcnt(" #n ")" ::: "memory")
; #define PG8_BAR __builtin_amdgcn_s_barrier()
; #define PG8_SCHED __builtin_amdgcn_sched_barrier(0)
; template <class Epi, class Sched>
; __device__ __forceinline__ void gemm_phase(LAS unsigned char* lds, const Gemm g, const Sched& S, const Epi& E, const int tid) {
;     ...
;             PG8_WAIT_V(8); PG8_WAIT_L(0); PG8_BAR; PG8_MMA(1, 0, At, B0); PG8_MMA(1, 1, At, B1); PG8_BAR; PG8_SCHED;
;             PG8_LDB(B0, 1, 0); PG8_LDB(B1, 1, 1); PG8_SCHED; PG8_LDA(At, 1, 0); PG8_STAGE(PG8_SA(0, 1), a2 + hstep, voffA);
;             PG8_WAIT_V(8); PG8_WAIT_L(0); PG8_BAR; PG8_MMA(0, 0, At, B0); PG8_MMA(0, 1, At, B1); PG8_BAR; PG8_SCHED;
	s_setprio 1
	s_waitcnt lgkmcnt(0)
	v_mfma_f32_16x16x32_bf16 v[60:63], v[70:73], v[202:205], 0
	v_mfma_f32_16x16x32_bf16 v[56:59], v[172:175], v[202:205], 0
	v_mfma_f32_16x16x32_bf16 v[52:55], v[70:73], v[210:213], 0
	v_mfma_f32_16x16x32_bf16 v[44:47], v[172:175], v[210:213], 0
	v_mfma_f32_16x16x32_bf16 v[28:31], v[70:73], v[218:221], 0
	v_mfma_f32_16x16x32_bf16 v[24:27], v[172:175], v[218:221], 0
	v_mfma_f32_16x16x32_bf16 v[16:19], v[70:73], v[234:237], 0
	v_mfma_f32_16x16x32_bf16 v[8:11], v[172:175], v[234:237], 0
	v_mfma_f32_16x16x32_bf16 v[60:63], v[74:77], v[206:209], v[60:63]
	v_mfma_f32_16x16x32_bf16 v[56:59], v[176:179], v[206:209], v[56:59]
	v_mfma_f32_16x16x32_bf16 v[52:55], v[74:77], v[214:217], v[52:55]
	v_mfma_f32_16x16x32_bf16 v[44:47], v[176:179], v[214:217], v[44:47]
	v_mfma_f32_16x16x32_bf16 v[28:31], v[74:77], v[230:233], v[28:31]
	v_mfma_f32_16x16x32_bf16 v[24:27], v[176:179], v[230:233], v[24:27]
	v_mfma_f32_16x16x32_bf16 v[16:19], v[74:77], v[238:241], v[16:19]
	v_mfma_f32_16x16x32_bf16 v[8:11], v[176:179], v[238:241], v[8:11]
	s_setprio 0
	s_setprio 1
	v_mfma_f32_16x16x32_bf16 v[48:51], v[180:183], v[202:205], 0
	v_mfma_f32_16x16x32_bf16 v[40:43], v[188:191], v[202:205], 0
	v_mfma_f32_16x16x32_bf16 v[36:39], v[180:183], v[210:213], 0
	v_mfma_f32_16x16x32_bf16 v[32:35], v[188:191], v[210:213], 0
	v_mfma_f32_16x16x32_bf16 v[20:23], v[180:183], v[218:221], 0
	v_mfma_f32_16x16x32_bf16 v[12:15], v[188:191], v[218:221], 0
	v_mfma_f32_16x16x32_bf16 v[4:7], v[180:183], v[234:237], 0
	v_mfma_f32_16x16x32_bf16 v[0:3], v[188:191], v[234:237], 0
	v_mfma_f32_16x16x32_bf16 v[48:51], v[184:187], v[206:209], v[48:51]
	v_mfma_f32_16x16x32_bf16 v[40:43], v[198:201], v[206:209], v[40:43]
	v_mfma_f32_16x16x32_bf16 v[36:39], v[184:187], v[214:217], v[36:39]
	v_mfma_f32_16x16x32_bf16 v[32:35], v[198:201], v[214:217], v[32:35]
	v_mfma_f32_16x16x32_bf16 v[20:23], v[184:187], v[230:233], v[20:23]
	v_mfma_f32_16x16x32_bf16 v[12:15], v[198:201], v[230:233], v[12:15]
	v_mfma_f32_16x16x32_bf16 v[4:7], v[184:187], v[238:241], v[4:7]
	v_mfma_f32_16x16x32_bf16 v[0:3], v[198:201], v[238:241], v[0:3]
	s_setprio 0
	s_barrier
	s_add_i32 s82, 0, 0x18000
	v_add_u32_e32 v69, s82, v154
	s_add_i32 s83, 0, 0x1c000
	ds_read_b128 v[70:73], v69
	ds_read_b128 v[74:77], v69 offset:1024
	ds_read_b128 v[172:175], v69 offset:2048
	ds_read_b128 v[176:179], v69 offset:3072
	v_add_u32_e32 v69, s83, v154
	ds_read_b128 v[180:183], v69
	ds_read_b128 v[184:187], v69 offset:1024
	ds_read_b128 v[188:191], v69 offset:2048
	ds_read_b128 v[198:201], v69 offset:3072
	s_add_u32 s66, s66, 0x40000
	s_addc_u32 s67, s67, 0
	s_mov_b32 m0, s57
	v_lshl_add_u64 v[82:83], s[66:67], 0, v[162:163]
	ds_read_b128 v[202:205], v171 offset:32768
	ds_read_b128 v[206:209], v171 offset:33792
	ds_read_b128 v[210:213], v171 offset:34816
	ds_read_b128 v[214:217], v171 offset:35840
	ds_read_b128 v[218:221], v171 offset:36864
	ds_read_b128 v[230:233], v171 offset:37888
	ds_read_b128 v[234:237], v171 offset:38912
	ds_read_b128 v[238:241], v171 offset:39936
	global_load_lds_dwordx4 v[82:83], off
	v_lshl_add_u64 v[82:83], s[66:67], 0, v[166:167]
	s_mov_b32 m0, s58
	s_nop 0
	global_load_lds_dwordx4 v[82:83], off
	s_waitcnt vmcnt(8)
	s_waitcnt lgkmcnt(0)
	s_barrier
	s_setprio 1
	s_waitcnt lgkmcnt(0)
	v_mfma_f32_16x16x32_bf16 v[140:143], v[70:73], v[202:205], v[140:143]
	v_mfma_f32_16x16x32_bf16 v[136:139], v[172:175], v[202:205], v[136:139]
	v_mfma_f32_16x16x32_bf16 v[132:135], v[70:73], v[210:213], v[132:135]
	v_mfma_f32_16x16x32_bf16 v[128:131], v[172:175], v[210:213], v[128:131]
	v_mfma_f32_16x16x32_bf16 v[116:119], v[70:73], v[218:221], v[116:119]
	v_mfma_f32_16x16x32_bf16 v[112:115], v[172:175], v[218:221], v[112:115]
	v_mfma_f32_16x16x32_bf16 v[100:103], v[70:73], v[234:237], v[100:103]
	v_mfma_f32_16x16x32_bf16 v[96:99], v[172:175], v[234:237], v[96:99]
	v_mfma_f32_16x16x32_bf16 v[140:143], v[74:77], v[206:209], v[140:143]
	v_mfma_f32_16x16x32_bf16 v[136:139], v[176:179], v[206:209], v[136:139]
	v_mfma_f32_16x16x32_bf16 v[132:135], v[74:77], v[214:217], v[132:135]
	v_mfma_f32_16x16x32_bf16 v[128:131], v[176:179], v[214:217], v[128:131]
	v_mfma_f32_16x16x32_bf16 v[116:119], v[74:77], v[230:233], v[116:119]
	v_mfma_f32_16x16x32_bf16 v[112:115], v[176:179], v[230:233], v[112:115]
	v_mfma_f32_16x16x32_bf16 v[100:103], v[74:77], v[238:241], v[100:103]
	v_mfma_f32_16x16x32_bf16 v[96:99], v[176:179], v[238:241], v[96:99]
	s_setprio 0
	s_setprio 1
	v_mfma_f32_16x16x32_bf16 v[124:127], v[180:183], v[202:205], v[124:127]
	v_mfma_f32_16x16x32_bf16 v[120:123], v[188:191], v[202:205], v[120:123]
	v_mfma_f32_16x16x32_bf16 v[108:111], v[180:183], v[210:213], v[108:111]
	v_mfma_f32_16x16x32_bf16 v[104:107], v[188:191], v[210:213], v[104:107]
	v_mfma_f32_16x16x32_bf16 v[92:95], v[180:183], v[218:221], v[92:95]
	v_mfma_f32_16x16x32_bf16 v[88:91], v[188:191], v[218:221], v[88:91]
	v_mfma_f32_16x16x32_bf16 v[82:85], v[180:183], v[234:237], v[84:87]
	v_mfma_f32_16x16x32_bf16 v[78:81], v[188:191], v[234:237], v[78:81]
	v_mfma_f32_16x16x32_bf16 v[124:127], v[184:187], v[206:209], v[124:127]
	v_mfma_f32_16x16x32_bf16 v[120:123], v[198:201], v[206:209], v[120:123]
	v_mfma_f32_16x16x32_bf16 v[108:111], v[184:187], v[214:217], v[108:111]
	v_mfma_f32_16x16x32_bf16 v[104:107], v[198:201], v[214:217], v[104:107]
	v_mfma_f32_16x16x32_bf16 v[92:95], v[184:187], v[230:233], v[92:95]
	v_mfma_f32_16x16x32_bf16 v[88:91], v[198:201], v[230:233], v[88:91]
	v_mfma_f32_16x16x32_bf16 v[84:87], v[184:187], v[238:241], v[82:85]
	v_mfma_f32_16x16x32_bf16 v[80:83], v[198:201], v[238:241], v[78:81]
	s_setprio 0
	s_barrier
; #define PG8_STAGE(bufoff, gbase, voff) do { _Pragma("unroll") for (int _i = 0; _i < 2; ++_i) \
;         __builtin_amdgcn_global_load_lds((const unsigned*)((const char*)(gbase) + (voff)[_i]), (LAS unsigned*)(lds + (bufoff) + ldsw + _i * 8192), 16, 0, 0); } while (0)
; #define PG8_LDA(dst, b, h) do { _Pragma("unroll") for (int m = 0; m < 4; ++m) _Pragma("unroll") for (int k = 0; k < 2; ++k) dst[m][k] = *(const LAS bf16x8*)(lds + PG8_SA(b, h) + aoff + m * 2048 + k * 1024); } while (0)
; #define PG8_MMA(ai, bj, At, Bt) do { __builtin_amdgcn_s_setprio(1); _Pragma("unroll") for (int m = 0; m < 4; ++m) _Pragma("unroll") for (int n = 0; n < 2; ++n) _Pragma("unroll") for (int k = 0; k < 2; ++k) \
;         acc[ai][bj][m][n] = __builtin_amdgcn_mfma_f32_16x16x32_bf16(Bt[n][k], At[m][k], acc[ai][bj][m][n], 0, 0, 0); __builtin_amdgcn_s_setprio(0); } while (0)
; #define PG8_WAIT_V(n) asm volatile("s_waitcnt vmcnt(" #n ")" ::: "memory")
; #define PG8_WAIT_L(n) asm volatile("s_waitcnt lgkmcnt(" #n ")" ::: "memory")
; #define PG8_BAR __builtin_amdgcn_s_barrier()
; #define PG8_SCHED __builtin_amdgcn_sched_barrier(0)
; template <class Epi, class Sched>
; __device__ __forceinline__ void gemm_phase(LAS unsigned char* lds, const Gemm g, const Sched& S, const Epi& E, const int tid) {
;     ...
;             PG8_LDA(At, 1, 1); PG8_STAGE(PG8_SB(1, 0), b3, voffB); PG8_STAGE(PG8_SB(1, 1), b3 + hstep, voffB); PG8_STAGE(PG8_SA(1, 0), a3, voffA);
;             PG8_WAIT_V(8); PG8_WAIT_L(0); PG8_BAR; PG8_MMA(1, 0, At, B0); PG8_MMA(1, 1, At, B1); PG8_BAR; PG8_SCHED;
;         }
	s_add_i32 s66, s82, s52
	v_lshl_add_u64 v[78:79], v[224:225], 0, s[68:69]
	s_mov_b32 m0, s66
	ds_read_b128 v[202:205], v171 offset:49152
	ds_read_b128 v[206:209], v171 offset:50176
	ds_read_b128 v[210:213], v171 offset:51200
	ds_read_b128 v[214:217], v171 offset:52224
	ds_read_b128 v[218:221], v171 offset:53248
	ds_read_b128 v[230:233], v171 offset:54272
	ds_read_b128 v[234:237], v171 offset:55296
	ds_read_b128 v[238:241], v171 offset:56320
	global_load_lds_dwordx4 v[78:79], off
	s_add_i32 m0, s66, 0x2000
	s_add_u32 s64, s64, 0x40080
	v_lshl_add_u64 v[78:79], v[226:227], 0, s[68:69]
	s_addc_u32 s65, s65, 0
	s_add_i32 s66, s83, s52
	global_load_lds_dwordx4 v[78:79], off
	v_lshl_add_u64 v[78:79], s[64:65], 0, v[164:165]
	s_mov_b32 m0, s66
	s_nop 0
	global_load_lds_dwordx4 v[78:79], off
	v_lshl_add_u64 v[78:79], s[64:65], 0, v[168:169]
	s_add_i32 m0, s66, 0x2000
	s_nop 0
	global_load_lds_dwordx4 v[78:79], off
	v_lshl_add_u64 v[78:79], v[242:243], 0, s[68:69]
	s_mov_b32 m0, s61
	s_nop 0
	global_load_lds_dwordx4 v[78:79], off
	v_lshl_add_u64 v[78:79], v[244:245], 0, s[68:69]
	s_mov_b32 m0, s70
	s_nop 0
	global_load_lds_dwordx4 v[78:79], off
	s_waitcnt vmcnt(8)
	s_waitcnt lgkmcnt(0)
	s_barrier
	s_setprio 1
	s_waitcnt lgkmcnt(0)
	v_mfma_f32_16x16x32_bf16 v[60:63], v[70:73], v[202:205], v[60:63]
	v_mfma_f32_16x16x32_bf16 v[56:59], v[172:175], v[202:205], v[56:59]
	v_mfma_f32_16x16x32_bf16 v[52:55], v[70:73], v[210:213], v[52:55]
	v_mfma_f32_16x16x32_bf16 v[44:47], v[172:175], v[210:213], v[44:47]
	v_mfma_f32_16x16x32_bf16 v[28:31], v[70:73], v[218:221], v[28:31]
	v_mfma_f32_16x16x32_bf16 v[24:27], v[172:175], v[218:221], v[24:27]
	v_mfma_f32_16x16x32_bf16 v[16:19], v[70:73], v[234:237], v[16:19]
	v_mfma_f32_16x16x32_bf16 v[8:11], v[172:175], v[234:237], v[8:11]
	v_mfma_f32_16x16x32_bf16 v[60:63], v[74:77], v[206:209], v[60:63]
	v_mfma_f32_16x16x32_bf16 v[56:59], v[176:179], v[206:209], v[56:59]
	v_mfma_f32_16x16x32_bf16 v[52:55], v[74:77], v[214:217], v[52:55]
	v_mfma_f32_16x16x32_bf16 v[44:47], v[176:179], v[214:217], v[44:47]
	v_mfma_f32_16x16x32_bf16 v[28:31], v[74:77], v[230:233], v[28:31]
	v_mfma_f32_16x16x32_bf16 v[24:27], v[176:179], v[230:233], v[24:27]
	v_mfma_f32_16x16x32_bf16 v[16:19], v[74:77], v[238:241], v[16:19]
	v_mfma_f32_16x16x32_bf16 v[8:11], v[176:179], v[238:241], v[8:11]
	s_setprio 0
	s_setprio 1
	v_mfma_f32_16x16x32_bf16 v[48:51], v[180:183], v[202:205], v[48:51]
	v_mfma_f32_16x16x32_bf16 v[40:43], v[188:191], v[202:205], v[40:43]
	v_mfma_f32_16x16x32_bf16 v[36:39], v[180:183], v[210:213], v[36:39]
	v_mfma_f32_16x16x32_bf16 v[32:35], v[188:191], v[210:213], v[32:35]
	v_mfma_f32_16x16x32_bf16 v[20:23], v[180:183], v[218:221], v[20:23]
	v_mfma_f32_16x16x32_bf16 v[12:15], v[188:191], v[218:221], v[12:15]
	v_mfma_f32_16x16x32_bf16 v[4:7], v[180:183], v[234:237], v[4:7]
	v_mfma_f32_16x16x32_bf16 v[0:3], v[188:191], v[234:237], v[0:3]
	v_mfma_f32_16x16x32_bf16 v[48:51], v[184:187], v[206:209], v[48:51]
	v_mfma_f32_16x16x32_bf16 v[40:43], v[198:201], v[206:209], v[40:43]
	v_mfma_f32_16x16x32_bf16 v[36:39], v[184:187], v[214:217], v[36:39]
	v_mfma_f32_16x16x32_bf16 v[32:35], v[198:201], v[214:217], v[32:35]
	v_mfma_f32_16x16x32_bf16 v[20:23], v[184:187], v[230:233], v[20:23]
	v_mfma_f32_16x16x32_bf16 v[12:15], v[198:201], v[230:233], v[12:15]
	v_mfma_f32_16x16x32_bf16 v[4:7], v[184:187], v[238:241], v[4:7]
	v_mfma_f32_16x16x32_bf16 v[0:3], v[198:201], v[238:241], v[0:3]
	s_setprio 0
	s_barrier
	s_add_i32 s81, s81, 2
	s_add_u32 s62, s62, 0x100
	s_addc_u32 s63, s63, 0
	s_add_u32 s78, s78, 0x100
	s_addc_u32 s79, s79, 0
	s_cmp_gt_u32 s81, 13

;     __device__ __forceinline__ Pre prefetch(const Unit& u, int tid) const { return prenorm_load(stats, u.pn * BM, sW + (size_t)(u.pn >> 4) * SW_ROWS + u.pm * BM, tid); }
;     __device__ __forceinline__ Pre prefetch(const Unit& u, int tid) const { return prenorm_load(stats, u.pm * BM, sW + (size_t)(u.pm >> 4) * SW_ROWS + u.pn * BM, tid); }
;     __device__ __forceinline__ Pre prefetch(const Unit& u, int tid) const { return prenorm_load(stats, u.pm * BM, sW + (size_t)(u.pm >> 4) * SW_ROWS + u.pn * BM, tid); }
; #define PG8_STAGE(bufoff, gbase, voff) do { _Pragma("unroll") for (int _i = 0; _i < 2; ++_i) \
;         __builtin_amdgcn_global_load_lds((const unsigned*)((const char*)(gbase) + (voff)[_i]), (LAS unsigned*)(lds + (bufoff) + ldsw + _i * 8192), 16, 0, 0); } while (0)
; #define PG8_LDA(dst, b, h) do { _Pragma("unroll") for (int m = 0; m < 4; ++m) _Pragma("unroll") for (int k = 0; k < 2; ++k) dst[m][k] = *(const LAS bf16x8*)(lds + PG8_SA(b, h) + aoff + m * 2048 + k * 1024); } while (0)
; #define PG8_WAIT_V(n) asm volatile("s_waitcnt vmcnt(" #n ")" ::: "memory")
; template <class Epi, class Sched>
; __device__ __forceinline__ void gemm_phase(LAS unsigned char* lds, const Gemm g, const Sched& S, const Epi& E, const int tid) {
;     ...
;         const bool has_next = S.next(ui + 1, nxt);
;         const char* nA = has_next ? (const char*)g.A + (size_t)nxt.pm * tstep : cA; const char* nB = has_next ? (const char*)g.Bt + (size_t)nxt.pn * tstep : cB;
;         const typename Epi::Pre pre = E.prefetch(cur, tid);
;         for (int t = 0; t < nt; t += 2) {
;             const bool last = (t == nt - 2);
;             const char* a1 = cA + (size_t)(t + 1) * kstep;
;             const char* a2 = last ? nA : cA + (size_t)(t + 2) * kstep; const char* b2 = last ? nB : cB + (size_t)(t + 2) * kstep;
;             const char* a3 = a2 + kstep; const char* b3 = b2 + kstep;
;             PG8_LDB(B0, 0, 0); PG8_LDB(B1, 0, 1); PG8_SCHED; PG8_LDA(At, 0, 0); PG8_STAGE(PG8_SA(1, 1), a1 + hstep, voffA);
;             PG8_WAIT_V(8); PG8_WAIT_L(0); PG8_BAR; PG8_MMA(0, 0, At, B0); PG8_MMA(0, 1, At, B1); PG8_BAR; PG8_SCHED;
;             PG8_LDA(At, 0, 1); PG8_STAGE(PG8_SB(0, 0), b2, voffB); PG8_STAGE(PG8_SB(0, 1), b2 + hstep, voffB); PG8_STAGE(PG8_SA(0, 0), a2, voffA);
;             PG8_WAIT_V(8); PG8_WAIT_L(0); PG8_BAR; PG8_MMA(1, 0, At, B0); PG8_MMA(1, 1, At, B1); PG8_BAR; PG8_SCHED;
.LBB0_566:
	s_or_b64 exec, exec, s[82:83]
	s_add_u32 vcc_lo, s80, 0x80
	s_addc_u32 vcc_hi, s81, 0
	s_add_u32 s61, s74, 0x100
	s_addc_u32 s67, s75, 0
	s_mov_b32 s74, 0
	s_add_i32 s80, s74, 2
	s_add_u32 s81, vcc_lo, 0x80
	s_addc_u32 s75, vcc_hi, 0
	s_add_i32 s3, 0, 0x10000
	s_cmp_eq_u32 s57, s74
	s_cselect_b32 s75, s71, s75
	s_cselect_b32 s74, s70, s81
	v_add_u32_e32 v70, s3, v232
	s_cselect_b32 s83, s73, s67
	s_cselect_b32 s82, s72, s61
	s_add_i32 s81, 0, 0x14000
	ds_read_b128 v[58:61], v70
	ds_read_b128 v[62:65], v70 offset:1024
	ds_read_b128 v[66:69], v70 offset:2048
	ds_read_b128 v[80:83], v70 offset:3072
	v_add_u32_e32 v70, s81, v232
	ds_read_b128 v[84:87], v70
	ds_read_b128 v[88:91], v70 offset:1024
	ds_read_b128 v[92:95], v70 offset:2048
	ds_read_b128 v[152:155], v70 offset:3072
	v_lshl_add_u64 v[70:71], vcc, 0, v[204:205]
	s_add_i32 m0, s97, 0xc000
	ds_read_b128 v[164:167], v240
	ds_read_b128 v[168:171], v240 offset:1024
	ds_read_b128 v[172:175], v240 offset:2048
	ds_read_b128 v[176:179], v240 offset:3072
	ds_read_b128 v[180:183], v240 offset:4096
	ds_read_b128 v[184:187], v240 offset:5120
	ds_read_b128 v[188:191], v240 offset:6144
	ds_read_b128 v[208:211], v240 offset:7168
	global_load_lds_dwordx4 v[70:71], off
	v_lshl_add_u64 v[70:71], vcc, 0, v[206:207]
	s_add_i32 m0, s97, 0xe000
	s_nop 0
	global_load_lds_dwordx4 v[70:71], off
	s_waitcnt vmcnt(8)
	s_waitcnt lgkmcnt(0)
	s_barrier
	s_setprio 1
	s_waitcnt lgkmcnt(0)
	v_mfma_f32_16x16x32_bf16 v[160:163], v[58:61], v[164:167], 0
	v_mfma_f32_16x16x32_bf16 v[156:159], v[66:69], v[164:167], 0
	v_mfma_f32_16x16x32_bf16 v[140:143], v[58:61], v[172:175], 0
	v_mfma_f32_16x16x32_bf16 v[136:139], v[66:69], v[172:175], 0
	v_mfma_f32_16x16x32_bf16 v[124:127], v[58:61], v[180:183], 0
	v_mfma_f32_16x16x32_bf16 v[120:123], v[66:69], v[180:183], 0
	v_mfma_f32_16x16x32_bf16 v[108:111], v[58:61], v[188:191], 0
	v_mfma_f32_16x16x32_bf16 v[104:107], v[66:69], v[188:191], 0
	v_mfma_f32_16x16x32_bf16 v[160:163], v[62:65], v[168:171], v[160:163]
	v_mfma_f32_16x16x32_bf16 v[156:159], v[80:83], v[168:171], v[156:159]
	v_mfma_f32_16x16x32_bf16 v[140:143], v[62:65], v[176:179], v[140:143]
	v_mfma_f32_16x16x32_bf16 v[136:139], v[80:83], v[176:179], v[136:139]
	v_mfma_f32_16x16x32_bf16 v[124:127], v[62:65], v[184:187], v[124:127]
	v_mfma_f32_16x16x32_bf16 v[120:123], v[80:83], v[184:187], v[120:123]
	v_mfma_f32_16x16x32_bf16 v[108:111], v[62:65], v[208:211], v[108:111]
	v_mfma_f32_16x16x32_bf16 v[104:107], v[80:83], v[208:211], v[104:107]
	s_setprio 0
	s_setprio 1
	v_mfma_f32_16x16x32_bf16 v[148:151], v[84:87], v[164:167], 0
	v_mfma_f32_16x16x32_bf16 v[144:147], v[92:95], v[164:167], 0
	v_mfma_f32_16x16x32_bf16 v[132:135], v[84:87], v[172:175], 0
	v_mfma_f32_16x16x32_bf16 v[128:131], v[92:95], v[172:175], 0
	v_mfma_f32_16x16x32_bf16 v[116:119], v[84:87], v[180:183], 0
	v_mfma_f32_16x16x32_bf16 v[112:115], v[92:95], v[180:183], 0
	v_mfma_f32_16x16x32_bf16 v[100:103], v[84:87], v[188:191], 0
	v_mfma_f32_16x16x32_bf16 v[96:99], v[92:95], v[188:191], 0
	v_mfma_f32_16x16x32_bf16 v[148:151], v[88:91], v[168:171], v[148:151]
	v_mfma_f32_16x16x32_bf16 v[144:147], v[152:155], v[168:171], v[144:147]
	v_mfma_f32_16x16x32_bf16 v[132:135], v[88:91], v[176:179], v[132:135]
	v_mfma_f32_16x16x32_bf16 v[128:131], v[152:155], v[176:179], v[128:131]
	v_mfma_f32_16x16x32_bf16 v[116:119], v[88:91], v[184:187], v[116:119]
	v_mfma_f32_16x16x32_bf16 v[112:115], v[152:155], v[184:187], v[112:115]
	v_mfma_f32_16x16x32_bf16 v[100:103], v[88:91], v[208:211], v[100:103]
	v_mfma_f32_16x16x32_bf16 v[96:99], v[152:155], v[208:211], v[96:99]
	s_setprio 0
	s_barrier
	s_add_i32 s3, s3, s94
	v_lshl_add_u64 v[212:213], s[82:83], 0, v[192:193]
	s_mov_b32 m0, s3
	ds_read_b128 v[164:167], v240 offset:16384
	ds_read_b128 v[168:171], v240 offset:17408
	ds_read_b128 v[172:175], v240 offset:18432
	ds_read_b128 v[176:179], v240 offset:19456
	ds_read_b128 v[180:183], v240 offset:20480
	ds_read_b128 v[184:187], v240 offset:21504
	ds_read_b128 v[188:191], v240 offset:22528
	ds_read_b128 v[208:211], v240 offset:23552
	global_load_lds_dwordx4 v[212:213], off
	s_add_i32 m0, s3, 0x2000
	v_lshl_add_u64 v[214:215], s[82:83], 0, v[198:199]
	s_add_u32 s82, s82, s12
	s_addc_u32 s83, s83, 0
	s_add_i32 s3, s81, s94
	global_load_lds_dwordx4 v[214:215], off
	v_lshl_add_u64 v[216:217], s[82:83], 0, v[192:193]
	s_mov_b32 m0, s3
	v_lshl_add_u64 v[218:219], s[82:83], 0, v[198:199]
	global_load_lds_dwordx4 v[216:217], off
	s_add_i32 m0, s3, 0x2000
	v_lshl_add_u64 v[220:221], s[74:75], 0, v[202:203]
	global_load_lds_dwordx4 v[218:219], off
	s_mov_b32 m0, s97
	v_lshl_add_u64 v[224:225], s[74:75], 0, v[200:201]
	global_load_lds_dwordx4 v[220:221], off
	s_mov_b32 m0, s98
	s_nop 0
	global_load_lds_dwordx4 v[224:225], off
	s_waitcnt vmcnt(8)
	s_waitcnt lgkmcnt(0)
	s_barrier
; #define PG8_STAGE(bufoff, gbase, voff) do { _Pragma("unroll") for (int _i = 0; _i < 2; ++_i) \
;         __builtin_amdgcn_global_load_lds((const unsigned*)((const char*)(gbase) + (voff)[_i]), (LAS unsigned*)(lds + (bufoff) + ldsw + _i * 8192), 16, 0, 0); } while (0)
; #define PG8_LDA(dst, b, h) do { _Pragma("unroll") for (int m = 0; m < 4; ++m) _Pragma("unroll") for (int k = 0; k < 2; ++k) dst[m][k] = *(const LAS bf16x8*)(lds + PG8_SA(b, h) + aoff + m * 2048 + k * 1024); } while (0)
; #define PG8_LDB(dst, b, h) do { _Pragma("unroll") for (int n = 0; n < 2; ++n) _Pragma("unroll") for (int k = 0; k < 2; ++k) dst[n][k] = *(const LAS bf16x8*)(lds + PG8_SB(b, h) + boff + n * 2048 + k * 1024); } while (0)
; #define PG8_MMA(ai, bj, At, Bt) do { __builtin_amdgcn_s_setprio(1); _Pragma("unroll") for (int m = 0; m < 4; ++m) _Pragma("unroll") for (int n = 0; n < 2; ++n) _Pragma("unroll") for (int k = 0; k < 2; ++k) \
;         acc[ai][bj][m][n] = __builtin_amdgcn_mfma_f32_16x16x32_bf16(Bt[n][k], At[m][k], acc[ai][bj][m][n], 0, 0, 0); __builtin_amdgcn_s_setprio(0); } while (0)
; #define PG8_WAIT_V(n) asm volatile("s_waitcnt vmcnt(" #n ")" ::: "memory")
; #define PG8_WAIT_L(n) asm volatile("s_waitcnt lgkmcnt(" #n ")" ::: "memory")
; #define PG8_BAR __builtin_amdgcn_s_barrier()
; #define PG8_SCHED __builtin_amdgcn_sched_barrier(0)
; template <class Epi, class Sched>
; __device__ __forceinline__ void gemm_phase(LAS unsigned char* lds, const Gemm g, const Sched& S, const Epi& E, const int tid) {
;     ...
;             PG8_WAIT_V(8); PG8_WAIT_L(0); PG8_BAR; PG8_MMA(1, 0, At, B0); PG8_MMA(1, 1, At, B1); PG8_BAR; PG8_SCHED;
;             PG8_LDB(B0, 1, 0); PG8_LDB(B1, 1, 1); PG8_SCHED; PG8_LDA(At, 1, 0); PG8_STAGE(PG8_SA(0, 1), a2 + hstep, voffA);
;             PG8_WAIT_V(8); PG8_WAIT_L(0); PG8_BAR; PG8_MMA(0, 0, At, B0); PG8_MMA(0, 1, At, B1); PG8_BAR; PG8_SCHED;
	s_setprio 1
	s_waitcnt lgkmcnt(0)
	v_mfma_f32_16x16x32_bf16 v[76:79], v[58:61], v[164:167], 0
	v_mfma_f32_16x16x32_bf16 v[70:73], v[66:69], v[164:167], 0
	v_mfma_f32_16x16x32_bf16 v[44:47], v[58:61], v[172:175], 0
	v_mfma_f32_16x16x32_bf16 v[40:43], v[66:69], v[172:175], 0
	v_mfma_f32_16x16x32_bf16 v[28:31], v[58:61], v[180:183], 0
	v_mfma_f32_16x16x32_bf16 v[24:27], v[66:69], v[180:183], 0
	v_mfma_f32_16x16x32_bf16 v[12:15], v[58:61], v[188:191], 0
	v_mfma_f32_16x16x32_bf16 v[8:11], v[66:69], v[188:191], 0
	v_mfma_f32_16x16x32_bf16 v[76:79], v[62:65], v[168:171], v[76:79]
	v_mfma_f32_16x16x32_bf16 v[70:73], v[80:83], v[168:171], v[70:73]
	v_mfma_f32_16x16x32_bf16 v[44:47], v[62:65], v[176:179], v[44:47]
	v_mfma_f32_16x16x32_bf16 v[40:43], v[80:83], v[176:179], v[40:43]
	v_mfma_f32_16x16x32_bf16 v[28:31], v[62:65], v[184:187], v[28:31]
	v_mfma_f32_16x16x32_bf16 v[24:27], v[80:83], v[184:187], v[24:27]
	v_mfma_f32_16x16x32_bf16 v[12:15], v[62:65], v[208:211], v[12:15]
	v_mfma_f32_16x16x32_bf16 v[8:11], v[80:83], v[208:211], v[8:11]
	s_setprio 0
	s_setprio 1
	v_mfma_f32_16x16x32_bf16 v[52:55], v[84:87], v[164:167], 0
	v_mfma_f32_16x16x32_bf16 v[48:51], v[92:95], v[164:167], 0
	v_mfma_f32_16x16x32_bf16 v[36:39], v[84:87], v[172:175], 0
	v_mfma_f32_16x16x32_bf16 v[32:35], v[92:95], v[172:175], 0
	v_mfma_f32_16x16x32_bf16 v[20:23], v[84:87], v[180:183], 0
	v_mfma_f32_16x16x32_bf16 v[16:19], v[92:95], v[180:183], 0
	v_mfma_f32_16x16x32_bf16 v[4:7], v[84:87], v[188:191], 0
	v_mfma_f32_16x16x32_bf16 v[0:3], v[92:95], v[188:191], 0
	v_mfma_f32_16x16x32_bf16 v[52:55], v[88:91], v[168:171], v[52:55]
	v_mfma_f32_16x16x32_bf16 v[48:51], v[152:155], v[168:171], v[48:51]
	v_mfma_f32_16x16x32_bf16 v[36:39], v[88:91], v[176:179], v[36:39]
	v_mfma_f32_16x16x32_bf16 v[32:35], v[152:155], v[176:179], v[32:35]
	v_mfma_f32_16x16x32_bf16 v[20:23], v[88:91], v[184:187], v[20:23]
	v_mfma_f32_16x16x32_bf16 v[16:19], v[152:155], v[184:187], v[16:19]
	v_mfma_f32_16x16x32_bf16 v[4:7], v[88:91], v[208:211], v[4:7]
	v_mfma_f32_16x16x32_bf16 v[0:3], v[152:155], v[208:211], v[0:3]
	s_setprio 0
	s_barrier
	s_add_i32 s3, 0, 0x18000
	v_add_u32_e32 v74, s3, v232
	s_add_i32 s81, 0, 0x1c000
	ds_read_b128 v[58:61], v74
	ds_read_b128 v[62:65], v74 offset:1024
	ds_read_b128 v[66:69], v74 offset:2048
	ds_read_b128 v[80:83], v74 offset:3072
	v_add_u32_e32 v74, s81, v232
	ds_read_b128 v[84:87], v74
	ds_read_b128 v[88:91], v74 offset:1024
	ds_read_b128 v[92:95], v74 offset:2048
	ds_read_b128 v[152:155], v74 offset:3072
	s_add_u32 s74, s74, s12
	s_addc_u32 s75, s75, 0
	s_mov_b32 m0, s99
	v_lshl_add_u64 v[74:75], s[74:75], 0, v[202:203]
	ds_read_b128 v[164:167], v240 offset:32768
	ds_read_b128 v[168:171], v240 offset:33792
	ds_read_b128 v[172:175], v240 offset:34816
	ds_read_b128 v[176:179], v240 offset:35840
	ds_read_b128 v[180:183], v240 offset:36864
	ds_read_b128 v[184:187], v240 offset:37888
	ds_read_b128 v[188:191], v240 offset:38912
	ds_read_b128 v[208:211], v240 offset:39936
	global_load_lds_dwordx4 v[74:75], off
	v_lshl_add_u64 v[74:75], s[74:75], 0, v[200:201]
	s_mov_b32 m0, s78
	s_nop 0
	global_load_lds_dwordx4 v[74:75], off
	s_waitcnt vmcnt(8)
	s_waitcnt lgkmcnt(0)
	s_barrier
	s_setprio 1
	s_waitcnt lgkmcnt(0)
	v_mfma_f32_16x16x32_bf16 v[160:163], v[58:61], v[164:167], v[160:163]
	v_mfma_f32_16x16x32_bf16 v[156:159], v[66:69], v[164:167], v[156:159]
	v_mfma_f32_16x16x32_bf16 v[140:143], v[58:61], v[172:175], v[140:143]
	v_mfma_f32_16x16x32_bf16 v[136:139], v[66:69], v[172:175], v[136:139]
	v_mfma_f32_16x16x32_bf16 v[124:127], v[58:61], v[180:183], v[124:127]
	v_mfma_f32_16x16x32_bf16 v[120:123], v[66:69], v[180:183], v[120:123]
	v_mfma_f32_16x16x32_bf16 v[108:111], v[58:61], v[188:191], v[108:111]
	v_mfma_f32_16x16x32_bf16 v[104:107], v[66:69], v[188:191], v[104:107]
	v_mfma_f32_16x16x32_bf16 v[160:163], v[62:65], v[168:171], v[160:163]
	v_mfma_f32_16x16x32_bf16 v[156:159], v[80:83], v[168:171], v[156:159]
	v_mfma_f32_16x16x32_bf16 v[140:143], v[62:65], v[176:179], v[140:143]
	v_mfma_f32_16x16x32_bf16 v[136:139], v[80:83], v[176:179], v[136:139]
	v_mfma_f32_16x16x32_bf16 v[124:127], v[62:65], v[184:187], v[124:127]
	v_mfma_f32_16x16x32_bf16 v[120:123], v[80:83], v[184:187], v[120:123]
	v_mfma_f32_16x16x32_bf16 v[108:111], v[62:65], v[208:211], v[108:111]
	v_mfma_f32_16x16x32_bf16 v[104:107], v[80:83], v[208:211], v[104:107]
	s_setprio 0
	s_setprio 1
	v_mfma_f32_16x16x32_bf16 v[148:151], v[84:87], v[164:167], v[148:151]
	v_mfma_f32_16x16x32_bf16 v[144:147], v[92:95], v[164:167], v[144:147]
	v_mfma_f32_16x16x32_bf16 v[132:135], v[84:87], v[172:175], v[132:135]
	v_mfma_f32_16x16x32_bf16 v[128:131], v[92:95], v[172:175], v[128:131]
	v_mfma_f32_16x16x32_bf16 v[116:119], v[84:87], v[180:183], v[116:119]
	v_mfma_f32_16x16x32_bf16 v[112:115], v[92:95], v[180:183], v[112:115]
	v_mfma_f32_16x16x32_bf16 v[100:103], v[84:87], v[188:191], v[100:103]
	v_mfma_f32_16x16x32_bf16 v[96:99], v[92:95], v[188:191], v[96:99]
	v_mfma_f32_16x16x32_bf16 v[148:151], v[88:91], v[168:171], v[148:151]
	v_mfma_f32_16x16x32_bf16 v[144:147], v[152:155], v[168:171], v[144:147]
	v_mfma_f32_16x16x32_bf16 v[132:135], v[88:91], v[176:179], v[132:135]
	v_mfma_f32_16x16x32_bf16 v[128:131], v[152:155], v[176:179], v[128:131]
	v_mfma_f32_16x16x32_bf16 v[116:119], v[88:91], v[184:187], v[116:119]
	v_mfma_f32_16x16x32_bf16 v[112:115], v[152:155], v[184:187], v[112:115]
	v_mfma_f32_16x16x32_bf16 v[100:103], v[88:91], v[208:211], v[100:103]
	v_mfma_f32_16x16x32_bf16 v[96:99], v[152:155], v[208:211], v[96:99]
	s_setprio 0
	s_barrier
; #define PG8_STAGE(bufoff, gbase, voff) do { _Pragma("unroll") for (int _i = 0; _i < 2; ++_i) \
;         __builtin_amdgcn_global_load_lds((const unsigned*)((const char*)(gbase) + (voff)[_i]), (LAS unsigned*)(lds + (bufoff) + ldsw + _i * 8192), 16, 0, 0); } while (0)
; #define PG8_LDA(dst, b, h) do { _Pragma("unroll") for (int m = 0; m < 4; ++m) _Pragma("unroll") for (int k = 0; k < 2; ++k) dst[m][k] = *(const LAS bf16x8*)(lds + PG8_SA(b, h) + aoff + m * 2048 + k * 1024); } while (0)
; #define PG8_MMA(ai, bj, At, Bt) do { __builtin_amdgcn_s_setprio(1); _Pragma("unroll") for (int m = 0; m < 4; ++m) _Pragma("unroll") for (int n = 0; n < 2; ++n) _Pragma("unroll") for (int k = 0; k < 2; ++k) \
;         acc[ai][bj][m][n] = __builtin_amdgcn_mfma_f32_16x16x32_bf16(Bt[n][k], At[m][k], acc[ai][bj][m][n], 0, 0, 0); __builtin_amdgcn_s_setprio(0); } while (0)
; #define PG8_WAIT_V(n) asm volatile("s_waitcnt vmcnt(" #n ")" ::: "memory")
; #define PG8_WAIT_L(n) asm volatile("s_waitcnt lgkmcnt(" #n ")" ::: "memory")
; #define PG8_BAR __builtin_amdgcn_s_barrier()
; #define PG8_SCHED __builtin_amdgcn_sched_barrier(0)
; template <class Epi, class Sched>
; __device__ __forceinline__ void gemm_phase(LAS unsigned char* lds, const Gemm g, const Sched& S, const Epi& E, const int tid) {
;     ...
;             PG8_LDA(At, 1, 1); PG8_STAGE(PG8_SB(1, 0), b3, voffB); PG8_STAGE(PG8_SB(1, 1), b3 + hstep, voffB); PG8_STAGE(PG8_SA(1, 0), a3, voffA);
;             PG8_WAIT_V(8); PG8_WAIT_L(0); PG8_BAR; PG8_MMA(1, 0, At, B0); PG8_MMA(1, 1, At, B1); PG8_BAR; PG8_SCHED;
;         }
	s_add_i32 s3, s3, s94
	v_lshl_add_u64 v[74:75], v[212:213], 0, s[68:69]
	s_mov_b32 m0, s3
	ds_read_b128 v[164:167], v240 offset:49152
	ds_read_b128 v[168:171], v240 offset:50176
	ds_read_b128 v[172:175], v240 offset:51200
	ds_read_b128 v[176:179], v240 offset:52224
	ds_read_b128 v[180:183], v240 offset:53248
	ds_read_b128 v[184:187], v240 offset:54272
	ds_read_b128 v[188:191], v240 offset:55296
	ds_read_b128 v[208:211], v240 offset:56320
	global_load_lds_dwordx4 v[74:75], off
	v_lshl_add_u64 v[74:75], v[214:215], 0, s[68:69]
	s_add_i32 m0, s3, 0x2000
	s_add_i32 s3, s81, s94
	global_load_lds_dwordx4 v[74:75], off
	v_lshl_add_u64 v[74:75], v[216:217], 0, s[68:69]
	s_mov_b32 m0, s3
	s_nop 0
	global_load_lds_dwordx4 v[74:75], off
	v_lshl_add_u64 v[74:75], v[218:219], 0, s[68:69]
	s_add_i32 m0, s3, 0x2000
	s_nop 0
	global_load_lds_dwordx4 v[74:75], off
	v_lshl_add_u64 v[74:75], v[220:221], 0, s[68:69]
	s_mov_b32 m0, s53
	s_nop 0
	global_load_lds_dwordx4 v[74:75], off
	v_lshl_add_u64 v[74:75], v[224:225], 0, s[68:69]
	s_mov_b32 m0, s56
	s_nop 0
	global_load_lds_dwordx4 v[74:75], off
	s_waitcnt vmcnt(8)
	s_waitcnt lgkmcnt(0)
	s_barrier
	s_setprio 1
	s_waitcnt lgkmcnt(0)
	v_mfma_f32_16x16x32_bf16 v[74:77], v[58:61], v[164:167], v[76:79]
	v_mfma_f32_16x16x32_bf16 v[70:73], v[66:69], v[164:167], v[70:73]
	v_mfma_f32_16x16x32_bf16 v[44:47], v[58:61], v[172:175], v[44:47]
	v_mfma_f32_16x16x32_bf16 v[40:43], v[66:69], v[172:175], v[40:43]
	v_mfma_f32_16x16x32_bf16 v[28:31], v[58:61], v[180:183], v[28:31]
	v_mfma_f32_16x16x32_bf16 v[24:27], v[66:69], v[180:183], v[24:27]
	v_mfma_f32_16x16x32_bf16 v[12:15], v[58:61], v[188:191], v[12:15]
	v_mfma_f32_16x16x32_bf16 v[8:11], v[66:69], v[188:191], v[8:11]
	v_mfma_f32_16x16x32_bf16 v[76:79], v[62:65], v[168:171], v[74:77]
	v_mfma_f32_16x16x32_bf16 v[72:75], v[80:83], v[168:171], v[70:73]
	v_mfma_f32_16x16x32_bf16 v[44:47], v[62:65], v[176:179], v[44:47]
	v_mfma_f32_16x16x32_bf16 v[40:43], v[80:83], v[176:179], v[40:43]
	v_mfma_f32_16x16x32_bf16 v[28:31], v[62:65], v[184:187], v[28:31]
	v_mfma_f32_16x16x32_bf16 v[24:27], v[80:83], v[184:187], v[24:27]
	v_mfma_f32_16x16x32_bf16 v[12:15], v[62:65], v[208:211], v[12:15]
	v_mfma_f32_16x16x32_bf16 v[8:11], v[80:83], v[208:211], v[8:11]
	s_setprio 0
	s_setprio 1
	v_mfma_f32_16x16x32_bf16 v[52:55], v[84:87], v[164:167], v[52:55]
	v_mfma_f32_16x16x32_bf16 v[48:51], v[92:95], v[164:167], v[48:51]
	v_mfma_f32_16x16x32_bf16 v[36:39], v[84:87], v[172:175], v[36:39]
	v_mfma_f32_16x16x32_bf16 v[32:35], v[92:95], v[172:175], v[32:35]
	v_mfma_f32_16x16x32_bf16 v[20:23], v[84:87], v[180:183], v[20:23]
	v_mfma_f32_16x16x32_bf16 v[16:19], v[92:95], v[180:183], v[16:19]
	v_mfma_f32_16x16x32_bf16 v[4:7], v[84:87], v[188:191], v[4:7]
	v_mfma_f32_16x16x32_bf16 v[0:3], v[92:95], v[188:191], v[0:3]
	v_mfma_f32_16x16x32_bf16 v[52:55], v[88:91], v[168:171], v[52:55]
	v_mfma_f32_16x16x32_bf16 v[48:51], v[152:155], v[168:171], v[48:51]
	v_mfma_f32_16x16x32_bf16 v[36:39], v[88:91], v[176:179], v[36:39]
	v_mfma_f32_16x16x32_bf16 v[32:35], v[152:155], v[176:179], v[32:35]
	v_mfma_f32_16x16x32_bf16 v[20:23], v[88:91], v[184:187], v[20:23]
	v_mfma_f32_16x16x32_bf16 v[16:19], v[152:155], v[184:187], v[16:19]
	v_mfma_f32_16x16x32_bf16 v[4:7], v[88:91], v[208:211], v[4:7]
	v_mfma_f32_16x16x32_bf16 v[0:3], v[152:155], v[208:211], v[0:3]
	s_setprio 0
	s_barrier
	s_add_u32 vcc_lo, vcc_lo, 0x100
	s_addc_u32 vcc_hi, vcc_hi, 0
	s_add_u32 s61, s61, 0x100
	s_addc_u32 s67, s67, 0
	s_cmp_ge_u32 s80, s52
	s_mov_b32 s74, s80
